# adds: cross-lane max in the attention loop via permlane16/32 swaps instead of ds_bpermute; state-unit conv row loads issued up front into spare registers
# speedup vs baseline: 1.0469x; 1.0039x over previous
; #define LAS __attribute__((address_space(3)))
; __device__ __forceinline__ unsigned pk2(float lo, float hi) { unsigned r; asm volatile("v_cvt_pk_bf16_f32 %0, %1, %2" : "=v"(r) : "v"(lo), "v"(hi)); return r; }
; template <class Put>
; __device__ __forceinline__ void conv_pair32(const bf16* Pseq  , int L, int p0, int xch, const float* cw, const float* cb, const Put& put) {
;     float w0[5], w1[5];
; #pragma unroll
;     for (int k = 0; k < 5; ++k) { w0[k] = cw[k * 1024 + xch]; w1[k] = cw[k * 1024 + xch + 1]; }
;     const float b0 = cb[xch], b1 = cb[xch + 1];
;     float a0 = 0.f, a1 = 0.f, a2 = 0.f, a3 = 0.f, a4 = 0.f, c0 = 0.f, c1 = 0.f, c2 = 0.f, c3 = 0.f, c4 = 0.f;
; #pragma unroll
;     for (int i = 0; i < 36; ++i) {
;         const int pos = p0 + i - 2;
;         unsigned raw = 0u;
;         if (pos >= 0 && pos < L) raw = *(const unsigned*)(Pseq + (size_t)pos * LDP + xch);
; __device__ __forceinline__ void ssd_state_unit(const Params& p, int layer, LAS unsigned char* lds, int b, int cc, int g) {
;     ...
;     for (int it = tid; it < 192 * 4; it += NT) {
;         const int pr = it % 192, q = it / 192, c0 = pr * 2;
;         const bool isx = c0 < 256;
;         const int xch = isx ? g * 256 + c0 : 512 + g * 128 + (c0 - 256);
;         LAS unsigned char* dst = isx ? lds + SS_XT + c0 * XT_PITCH : lds + SS_B + (c0 - 256) * BN_PITCH;
;         const int pitch = isx ? XT_PITCH : BN_PITCH;
;         conv_pair32(Pm + (size_t)G.Rseq0 * LDP + C_BX, G.L, G.pos0 + q * 32, xch, cw, cb, [&](int l, float v0, float v1) {
;             const unsigned pk = pk2(v0, v1); const int ll = q * 32 + l;
;             *(LAS unsigned short*)(dst + ll * 2) = (unsigned short)(pk & 0xffffu); *(LAS unsigned short*)(dst + pitch + ll * 2) = (unsigned short)(pk >> 16); });
.LBB0_460:
	s_mov_b32 s0, 0x2aaaaaab
	v_mul_hi_i32 v4, v2, s0
	v_lshrrev_b32_e32 v5, 31, v4
	v_ashrrev_i32_e32 v4, 5, v4
	v_add_u32_e32 v21, v4, v5
	s_movk_i32 s0, 0xff40
	v_mad_u64_u32 v[4:5], s[0:1], v21, s0, v[2:3]
	s_movk_i32 s0, 0x80
	s_nop 0
	v_cmp_gt_i32_e32 vcc, s0, v4
	s_movk_i32 s0, 0x7f
	v_cmp_lt_i32_e64 s[0:1], s0, v4
	s_and_saveexec_b64 s[18:19], s[0:1]
	s_xor_b64 s[0:1], exec, s[18:19]
	s_movk_i32 s18, 0xc0
	v_mul_lo_u32 v4, v21, s18
	v_sub_u32_e32 v4, v2, v4
	s_movk_i32 s18, 0x220
	v_mul_lo_u32 v4, v4, s18
	v_add_u32_e32 v4, s33, v4
	v_add_u32_e32 v18, 0xfffef000, v4
	s_or_saveexec_b64 s[0:1], s[0:1]
	v_mov_b32_e32 v23, 0x110
	s_xor_b64 exec, exec, s[0:1]
	s_mov_b32 s18, 0xfffe7400
	v_mad_u64_u32 v[18:19], s[18:19], v21, s18, v[0:1]
	v_mov_b32_e32 v23, 0x108
	s_or_b64 exec, exec, s[0:1]
	v_mov_b32_e32 v4, s16
	v_mov_b32_e32 v5, s17
	s_movk_i32 s0, 0x180
	v_cndmask_b32_e32 v4, v4, v5, vcc
	v_mul_lo_u32 v5, v21, s0
	v_sub_u32_e32 v4, v4, v5
	v_add_u32_e32 v16, v3, v4
	v_ashrrev_i32_e32 v17, 31, v16
	v_readlane_b32 s0, v254, 38
	v_lshlrev_b64 v[4:5], 2, v[16:17]
	v_readlane_b32 s1, v254, 39
	v_lshl_add_u32 v19, v21, 5, s3
	v_add_u32_e32 v24, -2, v19
	v_lshl_add_u64 v[10:11], s[0:1], 0, v[4:5]
	v_add_co_u32_e32 v12, vcc, 0x1000, v10
	s_movk_i32 s0, 0x3000
	s_nop 0
	v_addc_co_u32_e32 v13, vcc, 0, v11, vcc
	v_add_co_u32_e32 v8, vcc, s0, v10
	v_readlane_b32 s0, v254, 40
	s_nop 0
	v_addc_co_u32_e32 v9, vcc, 0, v11, vcc
	v_add_co_u32_e32 v14, vcc, 0x4000, v10
	v_readlane_b32 s1, v254, 41
	s_nop 0
	v_addc_co_u32_e32 v15, vcc, 0, v11, vcc
	global_load_dwordx2 v[6:7], v[8:9], off offset:-4096
	s_nop 0
	global_load_dwordx2 v[8:9], v[8:9], off
	s_nop 0
	global_load_dwordx2 v[10:11], v[10:11], off
	s_nop 0
	global_load_dwordx2 v[12:13], v[12:13], off
	s_nop 0
	global_load_dwordx2 v[14:15], v[14:15], off
	v_lshl_add_u64 v[4:5], s[0:1], 0, v[4:5]
	global_load_dwordx2 v[4:5], v[4:5], off
	v_cmp_lt_i32_e32 vcc, 1, v19
	v_cmp_gt_u32_e64 s[0:1], s14, v24
	v_lshl_add_u64 v[16:17], v[16:17], 1, s[6:7]
	v_add_u32_e32 v229, 2, v19
	v_add_u32_e32 v229, 1, v229
	v_mad_u64_u32 v[230:231], s[18:19], v229, s50, v[16:17]
	global_load_dword v132, v[230:231], off
	v_add_u32_e32 v229, 1, v229
	v_mad_u64_u32 v[230:231], s[18:19], v229, s50, v[16:17]
	global_load_dword v133, v[230:231], off
	v_add_u32_e32 v229, 1, v229
	v_mad_u64_u32 v[230:231], s[18:19], v229, s50, v[16:17]
	global_load_dword v134, v[230:231], off
	v_add_u32_e32 v229, 1, v229
	v_mad_u64_u32 v[230:231], s[18:19], v229, s50, v[16:17]
	global_load_dword v135, v[230:231], off
	v_add_u32_e32 v229, 1, v229
	v_mad_u64_u32 v[230:231], s[18:19], v229, s50, v[16:17]
	global_load_dword v136, v[230:231], off
	v_add_u32_e32 v229, 1, v229
	v_mad_u64_u32 v[230:231], s[18:19], v229, s50, v[16:17]
	global_load_dword v137, v[230:231], off
	v_add_u32_e32 v229, 1, v229
	v_mad_u64_u32 v[230:231], s[18:19], v229, s50, v[16:17]
	global_load_dword v138, v[230:231], off
	v_add_u32_e32 v229, 1, v229
	v_mad_u64_u32 v[230:231], s[18:19], v229, s50, v[16:17]
	global_load_dword v139, v[230:231], off
	v_add_u32_e32 v229, 1, v229
	v_mad_u64_u32 v[230:231], s[18:19], v229, s50, v[16:17]
	global_load_dword v140, v[230:231], off
	v_add_u32_e32 v229, 1, v229
	v_mad_u64_u32 v[230:231], s[18:19], v229, s50, v[16:17]
	global_load_dword v141, v[230:231], off
	v_add_u32_e32 v229, 1, v229
	v_mad_u64_u32 v[230:231], s[18:19], v229, s50, v[16:17]
	global_load_dword v142, v[230:231], off
	v_add_u32_e32 v229, 1, v229
	v_mad_u64_u32 v[230:231], s[18:19], v229, s50, v[16:17]
	global_load_dword v143, v[230:231], off
	v_add_u32_e32 v229, 1, v229
	v_mad_u64_u32 v[230:231], s[18:19], v229, s50, v[16:17]
	global_load_dword v144, v[230:231], off
	v_add_u32_e32 v229, 1, v229
	v_mad_u64_u32 v[230:231], s[18:19], v229, s50, v[16:17]
	global_load_dword v145, v[230:231], off
	v_add_u32_e32 v229, 1, v229
	v_mad_u64_u32 v[230:231], s[18:19], v229, s50, v[16:17]
	global_load_dword v146, v[230:231], off
	v_add_u32_e32 v229, 1, v229
	v_mad_u64_u32 v[230:231], s[18:19], v229, s50, v[16:17]
	global_load_dword v147, v[230:231], off
	v_add_u32_e32 v229, 1, v229
	v_mad_u64_u32 v[230:231], s[18:19], v229, s50, v[16:17]
	global_load_dword v148, v[230:231], off
	v_add_u32_e32 v229, 1, v229
	v_mad_u64_u32 v[230:231], s[18:19], v229, s50, v[16:17]
	global_load_dword v149, v[230:231], off
	v_add_u32_e32 v229, 1, v229
	v_mad_u64_u32 v[230:231], s[18:19], v229, s50, v[16:17]
	global_load_dword v150, v[230:231], off
	v_add_u32_e32 v229, 1, v229
	v_mad_u64_u32 v[230:231], s[18:19], v229, s50, v[16:17]
	global_load_dword v151, v[230:231], off
	v_add_u32_e32 v229, 1, v229
	v_mad_u64_u32 v[230:231], s[18:19], v229, s50, v[16:17]
	global_load_dword v152, v[230:231], off
	v_add_u32_e32 v229, 1, v229
	v_mad_u64_u32 v[230:231], s[18:19], v229, s50, v[16:17]
	global_load_dword v153, v[230:231], off
	v_add_u32_e32 v229, 1, v229
	v_mad_u64_u32 v[230:231], s[18:19], v229, s50, v[16:17]
	global_load_dword v154, v[230:231], off
	v_add_u32_e32 v229, 1, v229
	v_mad_u64_u32 v[230:231], s[18:19], v229, s50, v[16:17]
	global_load_dword v155, v[230:231], off
	v_add_u32_e32 v229, 1, v229
	v_mad_u64_u32 v[230:231], s[18:19], v229, s50, v[16:17]
	global_load_dword v156, v[230:231], off
	v_add_u32_e32 v229, 1, v229
	v_mad_u64_u32 v[230:231], s[18:19], v229, s50, v[16:17]
	global_load_dword v157, v[230:231], off
	v_add_u32_e32 v229, 1, v229
	v_mad_u64_u32 v[230:231], s[18:19], v229, s50, v[16:17]
	global_load_dword v158, v[230:231], off
	v_add_u32_e32 v229, 1, v229
	v_mad_u64_u32 v[230:231], s[18:19], v229, s50, v[16:17]
	global_load_dword v159, v[230:231], off
	v_add_u32_e32 v229, 1, v229
	v_mad_u64_u32 v[230:231], s[18:19], v229, s50, v[16:17]
	global_load_dword v160, v[230:231], off
	v_add_u32_e32 v229, 1, v229
	v_mad_u64_u32 v[230:231], s[18:19], v229, s50, v[16:17]
	global_load_dword v161, v[230:231], off
	v_add_u32_e32 v229, 1, v229
	v_mad_u64_u32 v[230:231], s[18:19], v229, s50, v[16:17]
	global_load_dword v162, v[230:231], off
	s_and_b64 s[18:19], vcc, s[0:1]
	v_mov_b32_e32 v27, 0
	v_mov_b32_e32 v22, 0
	s_and_saveexec_b64 s[0:1], s[18:19]
	s_cbranch_execz .LBB0_466
	v_mad_u64_u32 v[24:25], s[18:19], v24, s50, v[16:17]
	global_load_dword v22, v[24:25], off

; #define LAS __attribute__((address_space(3)))
; __device__ __forceinline__ unsigned pk2(float lo, float hi) { unsigned r; asm volatile("v_cvt_pk_bf16_f32 %0, %1, %2" : "=v"(r) : "v"(lo), "v"(hi)); return r; }
; __device__ __forceinline__ float lo16(unsigned w) { return __uint_as_float(w << 16); }
; __device__ __forceinline__ float hi16(unsigned w) { return __uint_as_float(w & 0xffff0000u); }
; __device__ __forceinline__ float siluf_(float x) { return x / (1.0f + __expf(-x)); }
; template <class Put>
; __device__ __forceinline__ void conv_pair32(const bf16* Pseq  , int L, int p0, int xch, const float* cw, const float* cb, const Put& put) {
;     ...
;     for (int i = 0; i < 36; ++i) {
;         const int pos = p0 + i - 2;
;         unsigned raw = 0u;
;         if (pos >= 0 && pos < L) raw = *(const unsigned*)(Pseq + (size_t)pos * LDP + xch);
;         a0 = a1; a1 = a2; a2 = a3; a3 = a4; a4 = lo16(raw);
;         c0 = c1; c1 = c2; c2 = c3; c3 = c4; c4 = hi16(raw);
;         if (i >= 4) {
;             const float v0 = b0 + w0[0] * a0 + w0[1] * a1 + w0[2] * a2 + w0[3] * a3 + w0[4] * a4;
;             const float v1 = b1 + w1[0] * c0 + w1[1] * c1 + w1[2] * c2 + w1[3] * c3 + w1[4] * c4;
;             put(i - 4, siluf_(v0), siluf_(v1));
;         }
; __device__ __forceinline__ void ssd_state_unit(const Params& p, int layer, LAS unsigned char* lds, int b, int cc, int g) {
;     ...
;         conv_pair32(Pm + (size_t)G.Rseq0 * LDP + C_BX, G.L, G.pos0 + q * 32, xch, cw, cb, [&](int l, float v0, float v1) {
;             const unsigned pk = pk2(v0, v1); const int ll = q * 32 + l;
;             *(LAS unsigned short*)(dst + ll * 2) = (unsigned short)(pk & 0xffffu); *(LAS unsigned short*)(dst + pitch + ll * 2) = (unsigned short)(pk >> 16); });
.LBB0_474:
	s_or_b64 exec, exec, s[0:1]
	s_waitcnt vmcnt(0)
	v_lshlrev_b32_e32 v33, 16, v22
	v_lshlrev_b32_e32 v32, 16, v27
	v_and_b32_e32 v29, 0xffff0000, v27
	v_and_b32_e32 v34, 0xffff0000, v22
	v_lshlrev_b32_e32 v27, 16, v28
	v_and_b32_e32 v22, 0xffff0000, v28
	v_fma_f32 v28, v10, v33, v4
	v_lshlrev_b32_e32 v30, 16, v25
	v_fmac_f32_e32 v28, v12, v32
	v_lshlrev_b32_e32 v31, 16, v26
	v_fmac_f32_e32 v28, v6, v30
	v_fmac_f32_e32 v28, v8, v31
	v_fmac_f32_e32 v28, v14, v27
	v_fma_f32 v33, v11, v34, v5
	v_mul_f32_e32 v34, 0xbfb8aa3b, v28
	v_exp_f32_e32 v34, v34
	v_and_b32_e32 v25, 0xffff0000, v25
	v_fmac_f32_e32 v33, v13, v29
	v_and_b32_e32 v26, 0xffff0000, v26
	v_add_f32_e32 v34, 1.0, v34
	v_div_scale_f32 v35, s[0:1], v34, v34, v28
	v_rcp_f32_e32 v36, v35
	v_fmac_f32_e32 v33, v7, v25
	v_fmac_f32_e32 v33, v9, v26
	v_fmac_f32_e32 v33, v15, v22
	v_fma_f32 v37, -v35, v36, 1.0
	v_fmac_f32_e32 v36, v37, v36
	v_div_scale_f32 v37, vcc, v28, v34, v28
	v_mul_f32_e32 v38, v37, v36
	v_fma_f32 v39, -v35, v38, v37
	v_fmac_f32_e32 v38, v39, v36
	v_fma_f32 v35, -v35, v38, v37
	v_div_fmas_f32 v35, v35, v36, v38
	v_div_fixup_f32 v28, v35, v34, v28
	v_mul_f32_e32 v34, 0xbfb8aa3b, v33
	v_exp_f32_e32 v34, v34
	s_nop 0
	v_add_f32_e32 v34, 1.0, v34
	v_div_scale_f32 v35, s[0:1], v34, v34, v33
	v_rcp_f32_e32 v36, v35
	s_nop 0
	v_fma_f32 v37, -v35, v36, 1.0
	v_fmac_f32_e32 v36, v37, v36
	v_div_scale_f32 v37, vcc, v33, v34, v33
	v_mul_f32_e32 v38, v37, v36
	v_fma_f32 v39, -v35, v38, v37
	v_fmac_f32_e32 v38, v39, v36
	v_fma_f32 v35, -v35, v38, v37
	v_div_fmas_f32 v35, v35, v36, v38
	v_div_fixup_f32 v33, v35, v34, v33
	v_cvt_pk_bf16_f32 v28, v28, v33
	v_lshlrev_b32_e32 v33, 6, v21
	v_add_u32_e32 v21, v18, v33
	v_add_u32_e32 v18, v18, v23
	v_add_u32_e32 v23, 3, v19
	v_cmp_lt_i32_e32 vcc, -4, v19
	v_cmp_gt_u32_e64 s[0:1], s14, v23
	v_add_u32_e32 v18, v18, v33
	s_and_b64 s[18:19], vcc, s[0:1]
	ds_write_b16 v21, v28
	ds_write_b16_d16_hi v18, v28
	s_and_saveexec_b64 s[0:1], s[18:19]
	s_cbranch_execz .LBB0_476
	v_mad_u64_u32 v[34:35], s[18:19], v23, s50, v[16:17]
	v_mov_b32_e32 v24, v132
.LBB0_476:
	s_or_b64 exec, exec, s[0:1]
	s_waitcnt vmcnt(0)
	v_lshlrev_b32_e32 v28, 16, v24
	v_and_b32_e32 v23, 0xffff0000, v24
	v_fma_f32 v24, v10, v32, v4
	v_fmac_f32_e32 v24, v12, v30
	v_fmac_f32_e32 v24, v6, v31
	v_fmac_f32_e32 v24, v8, v27
	v_fmac_f32_e32 v24, v14, v28
	v_mul_f32_e32 v32, 0xbfb8aa3b, v24
	v_exp_f32_e32 v32, v32
	v_fma_f32 v29, v11, v29, v5
	v_fmac_f32_e32 v29, v13, v25
	v_fmac_f32_e32 v29, v7, v26
	v_add_f32_e32 v32, 1.0, v32
	v_div_scale_f32 v33, s[0:1], v32, v32, v24
	v_rcp_f32_e32 v34, v33
	v_fmac_f32_e32 v29, v9, v22
	v_fmac_f32_e32 v29, v15, v23
	v_fma_f32 v35, -v33, v34, 1.0
	v_fmac_f32_e32 v34, v35, v34
	v_div_scale_f32 v35, vcc, v24, v32, v24
	v_mul_f32_e32 v36, v35, v34
	v_fma_f32 v37, -v33, v36, v35
	v_fmac_f32_e32 v36, v37, v34
	v_fma_f32 v33, -v33, v36, v35
	v_div_fmas_f32 v33, v33, v34, v36
	v_div_fixup_f32 v24, v33, v32, v24
	v_mul_f32_e32 v32, 0xbfb8aa3b, v29
	v_exp_f32_e32 v32, v32
	s_nop 0
	v_add_f32_e32 v32, 1.0, v32
	v_div_scale_f32 v33, s[0:1], v32, v32, v29
	v_rcp_f32_e32 v34, v33
	s_nop 0
	v_fma_f32 v35, -v33, v34, 1.0
	v_fmac_f32_e32 v34, v35, v34
	v_div_scale_f32 v35, vcc, v29, v32, v29
	v_mul_f32_e32 v36, v35, v34
	v_fma_f32 v37, -v33, v36, v35
	v_fmac_f32_e32 v36, v37, v34
	v_fma_f32 v33, -v33, v36, v35
	v_div_fmas_f32 v33, v33, v34, v36
	v_div_fixup_f32 v29, v33, v32, v29
	v_cvt_pk_bf16_f32 v24, v24, v29
	ds_write_b16 v21, v24 offset:2
	ds_write_b16_d16_hi v18, v24 offset:2
	v_add_u32_e32 v24, 4, v19
	v_cmp_lt_i32_e32 vcc, -5, v19
	v_cmp_gt_u32_e64 s[0:1], s14, v24
	s_and_b64 s[18:19], vcc, s[0:1]
	v_mov_b32_e32 v32, 0
	v_mov_b32_e32 v33, 0
	s_and_saveexec_b64 s[0:1], s[18:19]
	s_cbranch_execz .LBB0_478
	v_mad_u64_u32 v[34:35], s[18:19], v24, s50, v[16:17]
	v_mov_b32_e32 v33, v133
.LBB0_478:
	s_or_b64 exec, exec, s[0:1]
	v_fma_f32 v30, v10, v30, v4
	v_fmac_f32_e32 v30, v12, v31
	v_fmac_f32_e32 v30, v6, v27
	s_waitcnt vmcnt(0)
	v_lshlrev_b32_e32 v29, 16, v33
	v_fmac_f32_e32 v30, v8, v28
	v_fmac_f32_e32 v30, v14, v29
	v_and_b32_e32 v24, 0xffff0000, v33
	v_mul_f32_e32 v33, 0xbfb8aa3b, v30
	v_exp_f32_e32 v33, v33
	v_fma_f32 v25, v11, v25, v5
	v_fmac_f32_e32 v25, v13, v26
	v_fmac_f32_e32 v25, v7, v22
	v_add_f32_e32 v33, 1.0, v33
	v_div_scale_f32 v34, s[0:1], v33, v33, v30
	v_rcp_f32_e32 v35, v34
	v_fmac_f32_e32 v25, v9, v23
	v_fmac_f32_e32 v25, v15, v24
	v_fma_f32 v36, -v34, v35, 1.0
	v_fmac_f32_e32 v35, v36, v35
	v_div_scale_f32 v36, vcc, v30, v33, v30
	v_mul_f32_e32 v37, v36, v35
	v_fma_f32 v38, -v34, v37, v36
	v_fmac_f32_e32 v37, v38, v35
	v_fma_f32 v34, -v34, v37, v36
	v_div_fmas_f32 v34, v34, v35, v37
	v_div_fixup_f32 v30, v34, v33, v30
	v_mul_f32_e32 v33, 0xbfb8aa3b, v25
	v_exp_f32_e32 v33, v33
	s_nop 0
	v_add_f32_e32 v33, 1.0, v33
	v_div_scale_f32 v34, s[0:1], v33, v33, v25
	v_rcp_f32_e32 v35, v34
	s_nop 0
	v_fma_f32 v36, -v34, v35, 1.0
	v_fmac_f32_e32 v35, v36, v35
	v_div_scale_f32 v36, vcc, v25, v33, v25
	v_mul_f32_e32 v37, v36, v35
	v_fma_f32 v38, -v34, v37, v36
	v_fmac_f32_e32 v37, v38, v35
	v_fma_f32 v34, -v34, v37, v36
	v_div_fmas_f32 v34, v34, v35, v37
	v_div_fixup_f32 v25, v34, v33, v25
	v_cvt_pk_bf16_f32 v25, v30, v25
	ds_write_b16 v21, v25 offset:4
	ds_write_b16_d16_hi v18, v25 offset:4
	v_add_u32_e32 v25, 5, v19
	v_cmp_lt_i32_e32 vcc, -6, v19
	v_cmp_gt_u32_e64 s[0:1], s14, v25
	s_and_b64 s[18:19], vcc, s[0:1]
	s_and_saveexec_b64 s[0:1], s[18:19]
	s_cbranch_execz .LBB0_480
	v_mad_u64_u32 v[32:33], s[18:19], v25, s50, v[16:17]
	v_mov_b32_e32 v32, v134
; #define LAS __attribute__((address_space(3)))
; __device__ __forceinline__ unsigned pk2(float lo, float hi) { unsigned r; asm volatile("v_cvt_pk_bf16_f32 %0, %1, %2" : "=v"(r) : "v"(lo), "v"(hi)); return r; }
; __device__ __forceinline__ float lo16(unsigned w) { return __uint_as_float(w << 16); }
; __device__ __forceinline__ float hi16(unsigned w) { return __uint_as_float(w & 0xffff0000u); }
; __device__ __forceinline__ float siluf_(float x) { return x / (1.0f + __expf(-x)); }
; template <class Put>
; __device__ __forceinline__ void conv_pair32(const bf16* Pseq  , int L, int p0, int xch, const float* cw, const float* cb, const Put& put) {
;     ...
;     for (int i = 0; i < 36; ++i) {
;         const int pos = p0 + i - 2;
;         unsigned raw = 0u;
;         if (pos >= 0 && pos < L) raw = *(const unsigned*)(Pseq + (size_t)pos * LDP + xch);
;         a0 = a1; a1 = a2; a2 = a3; a3 = a4; a4 = lo16(raw);
;         c0 = c1; c1 = c2; c2 = c3; c3 = c4; c4 = hi16(raw);
;         if (i >= 4) {
;             const float v0 = b0 + w0[0] * a0 + w0[1] * a1 + w0[2] * a2 + w0[3] * a3 + w0[4] * a4;
;             const float v1 = b1 + w1[0] * c0 + w1[1] * c1 + w1[2] * c2 + w1[3] * c3 + w1[4] * c4;
;             put(i - 4, siluf_(v0), siluf_(v1));
;         }
; __device__ __forceinline__ void ssd_state_unit(const Params& p, int layer, LAS unsigned char* lds, int b, int cc, int g) {
;     ...
;         conv_pair32(Pm + (size_t)G.Rseq0 * LDP + C_BX, G.L, G.pos0 + q * 32, xch, cw, cb, [&](int l, float v0, float v1) {
;             const unsigned pk = pk2(v0, v1); const int ll = q * 32 + l;
;             *(LAS unsigned short*)(dst + ll * 2) = (unsigned short)(pk & 0xffffu); *(LAS unsigned short*)(dst + pitch + ll * 2) = (unsigned short)(pk >> 16); });
.LBB0_480:
	s_or_b64 exec, exec, s[0:1]
	v_fma_f32 v31, v10, v31, v4
	v_fmac_f32_e32 v31, v12, v27
	v_fmac_f32_e32 v31, v6, v28
	s_waitcnt vmcnt(0)
	v_lshlrev_b32_e32 v30, 16, v32
	v_fmac_f32_e32 v31, v8, v29
	v_fmac_f32_e32 v31, v14, v30
	v_and_b32_e32 v25, 0xffff0000, v32
	v_mul_f32_e32 v32, 0xbfb8aa3b, v31
	v_exp_f32_e32 v32, v32
	v_fma_f32 v26, v11, v26, v5
	v_fmac_f32_e32 v26, v13, v22
	v_fmac_f32_e32 v26, v7, v23
	v_add_f32_e32 v32, 1.0, v32
	v_div_scale_f32 v33, s[0:1], v32, v32, v31
	v_rcp_f32_e32 v34, v33
	v_fmac_f32_e32 v26, v9, v24
	v_fmac_f32_e32 v26, v15, v25
	v_fma_f32 v35, -v33, v34, 1.0
	v_fmac_f32_e32 v34, v35, v34
	v_div_scale_f32 v35, vcc, v31, v32, v31
	v_mul_f32_e32 v36, v35, v34
	v_fma_f32 v37, -v33, v36, v35
	v_fmac_f32_e32 v36, v37, v34
	v_fma_f32 v33, -v33, v36, v35
	v_div_fmas_f32 v33, v33, v34, v36
	v_div_fixup_f32 v31, v33, v32, v31
	v_mul_f32_e32 v32, 0xbfb8aa3b, v26
	v_exp_f32_e32 v32, v32
	s_nop 0
	v_add_f32_e32 v32, 1.0, v32
	v_div_scale_f32 v33, s[0:1], v32, v32, v26
	v_rcp_f32_e32 v34, v33
	s_nop 0
	v_fma_f32 v35, -v33, v34, 1.0
	v_fmac_f32_e32 v34, v35, v34
	v_div_scale_f32 v35, vcc, v26, v32, v26
	v_mul_f32_e32 v36, v35, v34
	v_fma_f32 v37, -v33, v36, v35
	v_fmac_f32_e32 v36, v37, v34
	v_fma_f32 v33, -v33, v36, v35
	v_div_fmas_f32 v33, v33, v34, v36
	v_div_fixup_f32 v26, v33, v32, v26
	v_cvt_pk_bf16_f32 v26, v31, v26
	ds_write_b16 v21, v26 offset:6
	ds_write_b16_d16_hi v18, v26 offset:6
	v_add_u32_e32 v26, 6, v19
	v_cmp_lt_i32_e32 vcc, -7, v19
	v_cmp_gt_u32_e64 s[0:1], s14, v26
	s_and_b64 s[18:19], vcc, s[0:1]
	v_mov_b32_e32 v33, 0
	v_mov_b32_e32 v32, 0
	s_and_saveexec_b64 s[0:1], s[18:19]
	s_cbranch_execz .LBB0_482
	v_mad_u64_u32 v[34:35], s[18:19], v26, s50, v[16:17]
	v_mov_b32_e32 v32, v135
.LBB0_482:
	s_or_b64 exec, exec, s[0:1]
	v_fma_f32 v27, v10, v27, v4
	v_fmac_f32_e32 v27, v12, v28
	v_fmac_f32_e32 v27, v6, v29
	s_waitcnt vmcnt(0)
	v_lshlrev_b32_e32 v31, 16, v32
	v_fmac_f32_e32 v27, v8, v30
	v_fmac_f32_e32 v27, v14, v31
	v_and_b32_e32 v26, 0xffff0000, v32
	v_mul_f32_e32 v32, 0xbfb8aa3b, v27
	v_exp_f32_e32 v32, v32
	v_fma_f32 v22, v11, v22, v5
	v_fmac_f32_e32 v22, v13, v23
	v_fmac_f32_e32 v22, v7, v24
	v_add_f32_e32 v32, 1.0, v32
	v_div_scale_f32 v34, s[0:1], v32, v32, v27
	v_rcp_f32_e32 v35, v34
	v_fmac_f32_e32 v22, v9, v25
	v_fmac_f32_e32 v22, v15, v26
	v_fma_f32 v36, -v34, v35, 1.0
	v_fmac_f32_e32 v35, v36, v35
	v_div_scale_f32 v36, vcc, v27, v32, v27
	v_mul_f32_e32 v37, v36, v35
	v_fma_f32 v38, -v34, v37, v36
	v_fmac_f32_e32 v37, v38, v35
	v_fma_f32 v34, -v34, v37, v36
	v_div_fmas_f32 v34, v34, v35, v37
	v_div_fixup_f32 v27, v34, v32, v27
	v_mul_f32_e32 v32, 0xbfb8aa3b, v22
	v_exp_f32_e32 v32, v32
	s_nop 0
	v_add_f32_e32 v32, 1.0, v32
	v_div_scale_f32 v34, s[0:1], v32, v32, v22
	v_rcp_f32_e32 v35, v34
	s_nop 0
	v_fma_f32 v36, -v34, v35, 1.0
	v_fmac_f32_e32 v35, v36, v35
	v_div_scale_f32 v36, vcc, v22, v32, v22
	v_mul_f32_e32 v37, v36, v35
	v_fma_f32 v38, -v34, v37, v36
	v_fmac_f32_e32 v37, v38, v35
	v_fma_f32 v34, -v34, v37, v36
	v_div_fmas_f32 v34, v34, v35, v37
	v_div_fixup_f32 v22, v34, v32, v22
	v_cvt_pk_bf16_f32 v22, v27, v22
	ds_write_b16 v21, v22 offset:8
	ds_write_b16_d16_hi v18, v22 offset:8
	v_add_u32_e32 v22, 7, v19
	v_cmp_lt_i32_e32 vcc, -8, v19
	v_cmp_gt_u32_e64 s[0:1], s14, v22
	s_and_b64 s[18:19], vcc, s[0:1]
	s_and_saveexec_b64 s[0:1], s[18:19]
	s_cbranch_execz .LBB0_484
	v_mad_u64_u32 v[32:33], s[18:19], v22, s50, v[16:17]
	v_mov_b32_e32 v33, v136
.LBB0_484:
	s_or_b64 exec, exec, s[0:1]
	v_fma_f32 v27, v10, v28, v4
	v_fmac_f32_e32 v27, v12, v29
	v_fmac_f32_e32 v27, v6, v30
	s_waitcnt vmcnt(0)
	v_lshlrev_b32_e32 v32, 16, v33
	v_fmac_f32_e32 v27, v8, v31
	v_fmac_f32_e32 v27, v14, v32
	v_mul_f32_e32 v28, 0xbfb8aa3b, v27
	v_exp_f32_e32 v28, v28
	v_and_b32_e32 v22, 0xffff0000, v33
	v_fma_f32 v23, v11, v23, v5
	v_fmac_f32_e32 v23, v13, v24
	v_add_f32_e32 v28, 1.0, v28
	v_div_scale_f32 v33, s[0:1], v28, v28, v27
	v_rcp_f32_e32 v34, v33
	v_fmac_f32_e32 v23, v7, v25
	v_fmac_f32_e32 v23, v9, v26
	v_fmac_f32_e32 v23, v15, v22
	v_fma_f32 v35, -v33, v34, 1.0
	v_fmac_f32_e32 v34, v35, v34
	v_div_scale_f32 v35, vcc, v27, v28, v27
	v_mul_f32_e32 v36, v35, v34
	v_fma_f32 v37, -v33, v36, v35
	v_fmac_f32_e32 v36, v37, v34
	v_fma_f32 v33, -v33, v36, v35
	v_div_fmas_f32 v33, v33, v34, v36
	v_div_fixup_f32 v27, v33, v28, v27
	v_mul_f32_e32 v28, 0xbfb8aa3b, v23
	v_exp_f32_e32 v28, v28
	s_nop 0
	v_add_f32_e32 v28, 1.0, v28
	v_div_scale_f32 v33, s[0:1], v28, v28, v23
	v_rcp_f32_e32 v34, v33
	s_nop 0
	v_fma_f32 v35, -v33, v34, 1.0
	v_fmac_f32_e32 v34, v35, v34
	v_div_scale_f32 v35, vcc, v23, v28, v23
	v_mul_f32_e32 v36, v35, v34
	v_fma_f32 v37, -v33, v36, v35
	v_fmac_f32_e32 v36, v37, v34
	v_fma_f32 v33, -v33, v36, v35
	v_div_fmas_f32 v33, v33, v34, v36
	v_div_fixup_f32 v23, v33, v28, v23
	v_cvt_pk_bf16_f32 v23, v27, v23
	ds_write_b16 v21, v23 offset:10
	ds_write_b16_d16_hi v18, v23 offset:10
	v_add_u32_e32 v23, 8, v19
	v_cmp_lt_i32_e32 vcc, -9, v19
	v_cmp_gt_u32_e64 s[0:1], s14, v23
	s_and_b64 s[18:19], vcc, s[0:1]
	v_mov_b32_e32 v27, 0
	v_mov_b32_e32 v28, 0
	s_and_saveexec_b64 s[0:1], s[18:19]
	s_cbranch_execz .LBB0_486
	v_mad_u64_u32 v[34:35], s[18:19], v23, s50, v[16:17]
	v_mov_b32_e32 v28, v137
; #define LAS __attribute__((address_space(3)))
; __device__ __forceinline__ unsigned pk2(float lo, float hi) { unsigned r; asm volatile("v_cvt_pk_bf16_f32 %0, %1, %2" : "=v"(r) : "v"(lo), "v"(hi)); return r; }
; __device__ __forceinline__ float lo16(unsigned w) { return __uint_as_float(w << 16); }
; __device__ __forceinline__ float hi16(unsigned w) { return __uint_as_float(w & 0xffff0000u); }
; __device__ __forceinline__ float siluf_(float x) { return x / (1.0f + __expf(-x)); }
; template <class Put>
; __device__ __forceinline__ void conv_pair32(const bf16* Pseq  , int L, int p0, int xch, const float* cw, const float* cb, const Put& put) {
;     ...
;     for (int i = 0; i < 36; ++i) {
;         const int pos = p0 + i - 2;
;         unsigned raw = 0u;
;         if (pos >= 0 && pos < L) raw = *(const unsigned*)(Pseq + (size_t)pos * LDP + xch);
;         a0 = a1; a1 = a2; a2 = a3; a3 = a4; a4 = lo16(raw);
;         c0 = c1; c1 = c2; c2 = c3; c3 = c4; c4 = hi16(raw);
;         if (i >= 4) {
;             const float v0 = b0 + w0[0] * a0 + w0[1] * a1 + w0[2] * a2 + w0[3] * a3 + w0[4] * a4;
;             const float v1 = b1 + w1[0] * c0 + w1[1] * c1 + w1[2] * c2 + w1[3] * c3 + w1[4] * c4;
;             put(i - 4, siluf_(v0), siluf_(v1));
;         }
; __device__ __forceinline__ void ssd_state_unit(const Params& p, int layer, LAS unsigned char* lds, int b, int cc, int g) {
;     ...
;         conv_pair32(Pm + (size_t)G.Rseq0 * LDP + C_BX, G.L, G.pos0 + q * 32, xch, cw, cb, [&](int l, float v0, float v1) {
;             const unsigned pk = pk2(v0, v1); const int ll = q * 32 + l;
;             *(LAS unsigned short*)(dst + ll * 2) = (unsigned short)(pk & 0xffffu); *(LAS unsigned short*)(dst + pitch + ll * 2) = (unsigned short)(pk >> 16); });
.LBB0_486:
	s_or_b64 exec, exec, s[0:1]
	s_waitcnt vmcnt(0)
	v_lshlrev_b32_e32 v33, 16, v28
	v_and_b32_e32 v23, 0xffff0000, v28
	v_fma_f32 v28, v10, v29, v4
	v_fmac_f32_e32 v28, v12, v30
	v_fmac_f32_e32 v28, v6, v31
	v_fmac_f32_e32 v28, v8, v32
	v_fmac_f32_e32 v28, v14, v33
	v_mul_f32_e32 v29, 0xbfb8aa3b, v28
	v_exp_f32_e32 v29, v29
	v_fma_f32 v24, v11, v24, v5
	v_fmac_f32_e32 v24, v13, v25
	v_fmac_f32_e32 v24, v7, v26
	v_add_f32_e32 v29, 1.0, v29
	v_div_scale_f32 v34, s[0:1], v29, v29, v28
	v_rcp_f32_e32 v35, v34
	v_fmac_f32_e32 v24, v9, v22
	v_fmac_f32_e32 v24, v15, v23
	v_fma_f32 v36, -v34, v35, 1.0
	v_fmac_f32_e32 v35, v36, v35
	v_div_scale_f32 v36, vcc, v28, v29, v28
	v_mul_f32_e32 v37, v36, v35
	v_fma_f32 v38, -v34, v37, v36
	v_fmac_f32_e32 v37, v38, v35
	v_fma_f32 v34, -v34, v37, v36
	v_div_fmas_f32 v34, v34, v35, v37
	v_div_fixup_f32 v28, v34, v29, v28
	v_mul_f32_e32 v29, 0xbfb8aa3b, v24
	v_exp_f32_e32 v29, v29
	s_nop 0
	v_add_f32_e32 v29, 1.0, v29
	v_div_scale_f32 v34, s[0:1], v29, v29, v24
	v_rcp_f32_e32 v35, v34
	s_nop 0
	v_fma_f32 v36, -v34, v35, 1.0
	v_fmac_f32_e32 v35, v36, v35
	v_div_scale_f32 v36, vcc, v24, v29, v24
	v_mul_f32_e32 v37, v36, v35
	v_fma_f32 v38, -v34, v37, v36
	v_fmac_f32_e32 v37, v38, v35
	v_fma_f32 v34, -v34, v37, v36
	v_div_fmas_f32 v34, v34, v35, v37
	v_div_fixup_f32 v24, v34, v29, v24
	v_cvt_pk_bf16_f32 v24, v28, v24
	ds_write_b16 v21, v24 offset:12
	ds_write_b16_d16_hi v18, v24 offset:12
	v_add_u32_e32 v24, 9, v19
	v_cmp_lt_i32_e32 vcc, -10, v19
	v_cmp_gt_u32_e64 s[0:1], s14, v24
	s_and_b64 s[18:19], vcc, s[0:1]
	s_and_saveexec_b64 s[0:1], s[18:19]
	s_cbranch_execz .LBB0_488
	v_mad_u64_u32 v[28:29], s[18:19], v24, s50, v[16:17]
	v_mov_b32_e32 v27, v138
.LBB0_488:
	s_or_b64 exec, exec, s[0:1]
	v_fma_f32 v24, v10, v30, v4
	v_fmac_f32_e32 v24, v12, v31
	v_fmac_f32_e32 v24, v6, v32
	s_waitcnt vmcnt(0)
	v_lshlrev_b32_e32 v34, 16, v27
	v_fmac_f32_e32 v24, v8, v33
	v_fmac_f32_e32 v24, v14, v34
	v_mul_f32_e32 v28, 0xbfb8aa3b, v24
	v_exp_f32_e32 v28, v28
	v_fma_f32 v25, v11, v25, v5
	v_fmac_f32_e32 v25, v13, v26
	v_fmac_f32_e32 v25, v7, v22
	v_add_f32_e32 v28, 1.0, v28
	v_div_scale_f32 v29, s[0:1], v28, v28, v24
	v_rcp_f32_e32 v30, v29
	v_and_b32_e32 v27, 0xffff0000, v27
	v_fmac_f32_e32 v25, v9, v23
	v_fmac_f32_e32 v25, v15, v27
	v_fma_f32 v35, -v29, v30, 1.0
	v_fmac_f32_e32 v30, v35, v30
	v_div_scale_f32 v35, vcc, v24, v28, v24
	v_mul_f32_e32 v36, v35, v30
	v_fma_f32 v37, -v29, v36, v35
	v_fmac_f32_e32 v36, v37, v30
	v_fma_f32 v29, -v29, v36, v35
	v_div_fmas_f32 v29, v29, v30, v36
	v_div_fixup_f32 v24, v29, v28, v24
	v_mul_f32_e32 v28, 0xbfb8aa3b, v25
	v_exp_f32_e32 v28, v28
	s_nop 0
	v_add_f32_e32 v28, 1.0, v28
	v_div_scale_f32 v29, s[0:1], v28, v28, v25
	v_rcp_f32_e32 v30, v29
	s_nop 0
	v_fma_f32 v35, -v29, v30, 1.0
	v_fmac_f32_e32 v30, v35, v30
	v_div_scale_f32 v35, vcc, v25, v28, v25
	v_mul_f32_e32 v36, v35, v30
	v_fma_f32 v37, -v29, v36, v35
	v_fmac_f32_e32 v36, v37, v30
	v_fma_f32 v29, -v29, v36, v35
	v_div_fmas_f32 v29, v29, v30, v36
	v_div_fixup_f32 v25, v29, v28, v25
	v_cvt_pk_bf16_f32 v24, v24, v25
	v_add_u32_e32 v25, 10, v19
	v_cmp_lt_i32_e32 vcc, -11, v19
	v_cmp_gt_u32_e64 s[0:1], s14, v25
	ds_write_b16 v21, v24 offset:14
	ds_write_b16_d16_hi v18, v24 offset:14
	s_and_b64 s[18:19], vcc, s[0:1]
	v_mov_b32_e32 v24, 0
	v_mov_b32_e32 v28, 0
	s_and_saveexec_b64 s[0:1], s[18:19]
	s_cbranch_execz .LBB0_490
	v_mad_u64_u32 v[28:29], s[18:19], v25, s50, v[16:17]
	v_mov_b32_e32 v28, v139
.LBB0_490:
	s_or_b64 exec, exec, s[0:1]
	v_fma_f32 v25, v10, v31, v4
	v_fmac_f32_e32 v25, v12, v32
	v_fmac_f32_e32 v25, v6, v33
	s_waitcnt vmcnt(0)
	v_lshlrev_b32_e32 v35, 16, v28
	v_fmac_f32_e32 v25, v8, v34
	v_fmac_f32_e32 v25, v14, v35
	v_mul_f32_e32 v29, 0xbfb8aa3b, v25
	v_exp_f32_e32 v29, v29
	v_fma_f32 v26, v11, v26, v5
	v_fmac_f32_e32 v26, v13, v22
	v_fmac_f32_e32 v26, v7, v23
	v_add_f32_e32 v29, 1.0, v29
	v_div_scale_f32 v30, s[0:1], v29, v29, v25
	v_rcp_f32_e32 v31, v30
	v_and_b32_e32 v28, 0xffff0000, v28
	v_fmac_f32_e32 v26, v9, v27
	v_fmac_f32_e32 v26, v15, v28
	v_fma_f32 v36, -v30, v31, 1.0
	v_fmac_f32_e32 v31, v36, v31
	v_div_scale_f32 v36, vcc, v25, v29, v25
	v_mul_f32_e32 v37, v36, v31
	v_fma_f32 v38, -v30, v37, v36
	v_fmac_f32_e32 v37, v38, v31
	v_fma_f32 v30, -v30, v37, v36
	v_div_fmas_f32 v30, v30, v31, v37
	v_div_fixup_f32 v25, v30, v29, v25
	v_mul_f32_e32 v29, 0xbfb8aa3b, v26
	v_exp_f32_e32 v29, v29
	s_nop 0
	v_add_f32_e32 v29, 1.0, v29
	v_div_scale_f32 v30, s[0:1], v29, v29, v26
	v_rcp_f32_e32 v31, v30
	s_nop 0
	v_fma_f32 v36, -v30, v31, 1.0
	v_fmac_f32_e32 v31, v36, v31
	v_div_scale_f32 v36, vcc, v26, v29, v26
	v_mul_f32_e32 v37, v36, v31
	v_fma_f32 v38, -v30, v37, v36
	v_fmac_f32_e32 v37, v38, v31
	v_fma_f32 v30, -v30, v37, v36
	v_div_fmas_f32 v30, v30, v31, v37
	v_div_fixup_f32 v26, v30, v29, v26
	v_cvt_pk_bf16_f32 v25, v25, v26
	ds_write_b16 v21, v25 offset:16
	ds_write_b16_d16_hi v18, v25 offset:16
	v_add_u32_e32 v25, 11, v19
	v_cmp_lt_i32_e32 vcc, -12, v19
	v_cmp_gt_u32_e64 s[0:1], s14, v25
	s_and_b64 s[18:19], vcc, s[0:1]
	s_and_saveexec_b64 s[0:1], s[18:19]
	s_cbranch_execz .LBB0_492
	v_mad_u64_u32 v[24:25], s[18:19], v25, s50, v[16:17]
	v_mov_b32_e32 v24, v140
; #define LAS __attribute__((address_space(3)))
; __device__ __forceinline__ unsigned pk2(float lo, float hi) { unsigned r; asm volatile("v_cvt_pk_bf16_f32 %0, %1, %2" : "=v"(r) : "v"(lo), "v"(hi)); return r; }
; __device__ __forceinline__ float lo16(unsigned w) { return __uint_as_float(w << 16); }
; __device__ __forceinline__ float hi16(unsigned w) { return __uint_as_float(w & 0xffff0000u); }
; __device__ __forceinline__ float siluf_(float x) { return x / (1.0f + __expf(-x)); }
; template <class Put>
; __device__ __forceinline__ void conv_pair32(const bf16* Pseq  , int L, int p0, int xch, const float* cw, const float* cb, const Put& put) {
;     ...
;     for (int i = 0; i < 36; ++i) {
;         const int pos = p0 + i - 2;
;         unsigned raw = 0u;
;         if (pos >= 0 && pos < L) raw = *(const unsigned*)(Pseq + (size_t)pos * LDP + xch);
;         a0 = a1; a1 = a2; a2 = a3; a3 = a4; a4 = lo16(raw);
;         c0 = c1; c1 = c2; c2 = c3; c3 = c4; c4 = hi16(raw);
;         if (i >= 4) {
;             const float v0 = b0 + w0[0] * a0 + w0[1] * a1 + w0[2] * a2 + w0[3] * a3 + w0[4] * a4;
;             const float v1 = b1 + w1[0] * c0 + w1[1] * c1 + w1[2] * c2 + w1[3] * c3 + w1[4] * c4;
;             put(i - 4, siluf_(v0), siluf_(v1));
;         }
; __device__ __forceinline__ void ssd_state_unit(const Params& p, int layer, LAS unsigned char* lds, int b, int cc, int g) {
;     ...
;         conv_pair32(Pm + (size_t)G.Rseq0 * LDP + C_BX, G.L, G.pos0 + q * 32, xch, cw, cb, [&](int l, float v0, float v1) {
;             const unsigned pk = pk2(v0, v1); const int ll = q * 32 + l;
;             *(LAS unsigned short*)(dst + ll * 2) = (unsigned short)(pk & 0xffffu); *(LAS unsigned short*)(dst + pitch + ll * 2) = (unsigned short)(pk >> 16); });
.LBB0_492:
	s_or_b64 exec, exec, s[0:1]
	s_waitcnt vmcnt(0)
	v_lshlrev_b32_e32 v36, 16, v24
	v_and_b32_e32 v29, 0xffff0000, v24
	v_fma_f32 v24, v10, v32, v4
	v_fmac_f32_e32 v24, v12, v33
	v_fmac_f32_e32 v24, v6, v34
	v_fmac_f32_e32 v24, v8, v35
	v_fmac_f32_e32 v24, v14, v36
	v_mul_f32_e32 v25, 0xbfb8aa3b, v24
	v_exp_f32_e32 v25, v25
	v_fma_f32 v22, v11, v22, v5
	v_fmac_f32_e32 v22, v13, v23
	v_fmac_f32_e32 v22, v7, v27
	v_add_f32_e32 v25, 1.0, v25
	v_div_scale_f32 v26, s[0:1], v25, v25, v24
	v_rcp_f32_e32 v30, v26
	v_fmac_f32_e32 v22, v9, v28
	v_fmac_f32_e32 v22, v15, v29
	v_fma_f32 v31, -v26, v30, 1.0
	v_fmac_f32_e32 v30, v31, v30
	v_div_scale_f32 v31, vcc, v24, v25, v24
	v_mul_f32_e32 v32, v31, v30
	v_fma_f32 v37, -v26, v32, v31
	v_fmac_f32_e32 v32, v37, v30
	v_fma_f32 v26, -v26, v32, v31
	v_div_fmas_f32 v26, v26, v30, v32
	v_div_fixup_f32 v24, v26, v25, v24
	v_mul_f32_e32 v25, 0xbfb8aa3b, v22
	v_exp_f32_e32 v25, v25
	s_nop 0
	v_add_f32_e32 v25, 1.0, v25
	v_div_scale_f32 v26, s[0:1], v25, v25, v22
	v_rcp_f32_e32 v30, v26
	s_nop 0
	v_fma_f32 v31, -v26, v30, 1.0
	v_fmac_f32_e32 v30, v31, v30
	v_div_scale_f32 v31, vcc, v22, v25, v22
	v_mul_f32_e32 v32, v31, v30
	v_fma_f32 v37, -v26, v32, v31
	v_fmac_f32_e32 v32, v37, v30
	v_fma_f32 v26, -v26, v32, v31
	v_div_fmas_f32 v26, v26, v30, v32
	v_div_fixup_f32 v22, v26, v25, v22
	v_cvt_pk_bf16_f32 v22, v24, v22
	v_add_u32_e32 v24, 12, v19
	v_cmp_lt_i32_e32 vcc, -13, v19
	v_cmp_gt_u32_e64 s[0:1], s14, v24
	ds_write_b16 v21, v22 offset:18
	ds_write_b16_d16_hi v18, v22 offset:18
	s_and_b64 s[18:19], vcc, s[0:1]
	v_mov_b32_e32 v22, 0
	v_mov_b32_e32 v25, 0
	s_and_saveexec_b64 s[0:1], s[18:19]
	s_cbranch_execz .LBB0_494
	v_mad_u64_u32 v[24:25], s[18:19], v24, s50, v[16:17]
	v_mov_b32_e32 v25, v141
.LBB0_494:
	s_or_b64 exec, exec, s[0:1]
	s_waitcnt vmcnt(0)
	v_lshlrev_b32_e32 v32, 16, v25
	v_and_b32_e32 v24, 0xffff0000, v25
	v_fma_f32 v25, v10, v33, v4
	v_fmac_f32_e32 v25, v12, v34
	v_fmac_f32_e32 v25, v6, v35
	v_fmac_f32_e32 v25, v8, v36
	v_fmac_f32_e32 v25, v14, v32
	v_mul_f32_e32 v26, 0xbfb8aa3b, v25
	v_exp_f32_e32 v26, v26
	v_fma_f32 v23, v11, v23, v5
	v_fmac_f32_e32 v23, v13, v27
	v_fmac_f32_e32 v23, v7, v28
	v_add_f32_e32 v26, 1.0, v26
	v_div_scale_f32 v30, s[0:1], v26, v26, v25
	v_rcp_f32_e32 v31, v30
	v_fmac_f32_e32 v23, v9, v29
	v_fmac_f32_e32 v23, v15, v24
	v_fma_f32 v33, -v30, v31, 1.0
	v_fmac_f32_e32 v31, v33, v31
	v_div_scale_f32 v33, vcc, v25, v26, v25
	v_mul_f32_e32 v37, v33, v31
	v_fma_f32 v38, -v30, v37, v33
	v_fmac_f32_e32 v37, v38, v31
	v_fma_f32 v30, -v30, v37, v33
	v_div_fmas_f32 v30, v30, v31, v37
	v_div_fixup_f32 v25, v30, v26, v25
	v_mul_f32_e32 v26, 0xbfb8aa3b, v23
	v_exp_f32_e32 v26, v26
	s_nop 0
	v_add_f32_e32 v26, 1.0, v26
	v_div_scale_f32 v30, s[0:1], v26, v26, v23
	v_rcp_f32_e32 v31, v30
	s_nop 0
	v_fma_f32 v33, -v30, v31, 1.0
	v_fmac_f32_e32 v31, v33, v31
	v_div_scale_f32 v33, vcc, v23, v26, v23
	v_mul_f32_e32 v37, v33, v31
	v_fma_f32 v38, -v30, v37, v33
	v_fmac_f32_e32 v37, v38, v31
	v_fma_f32 v30, -v30, v37, v33
	v_div_fmas_f32 v30, v30, v31, v37
	v_div_fixup_f32 v23, v30, v26, v23
	v_cvt_pk_bf16_f32 v23, v25, v23
	ds_write_b16 v21, v23 offset:20
	ds_write_b16_d16_hi v18, v23 offset:20
	v_add_u32_e32 v23, 13, v19
	v_cmp_lt_i32_e32 vcc, -14, v19
	v_cmp_gt_u32_e64 s[0:1], s14, v23
	s_and_b64 s[18:19], vcc, s[0:1]
	s_and_saveexec_b64 s[0:1], s[18:19]
	s_cbranch_execz .LBB0_496
	v_mad_u64_u32 v[22:23], s[18:19], v23, s50, v[16:17]
	v_mov_b32_e32 v22, v142
.LBB0_496:
	s_or_b64 exec, exec, s[0:1]
	s_waitcnt vmcnt(0)
	v_lshlrev_b32_e32 v30, 16, v22
	v_and_b32_e32 v25, 0xffff0000, v22
	v_fma_f32 v22, v10, v34, v4
	v_fmac_f32_e32 v22, v12, v35
	v_fmac_f32_e32 v22, v6, v36
	v_fmac_f32_e32 v22, v8, v32
	v_fmac_f32_e32 v22, v14, v30
	v_mul_f32_e32 v26, 0xbfb8aa3b, v22
	v_exp_f32_e32 v26, v26
	v_fma_f32 v23, v11, v27, v5
	v_fmac_f32_e32 v23, v13, v28
	v_fmac_f32_e32 v23, v7, v29
	v_add_f32_e32 v26, 1.0, v26
	v_div_scale_f32 v27, s[0:1], v26, v26, v22
	v_rcp_f32_e32 v31, v27
	v_fmac_f32_e32 v23, v9, v24
	v_fmac_f32_e32 v23, v15, v25
	v_fma_f32 v33, -v27, v31, 1.0
	v_fmac_f32_e32 v31, v33, v31
	v_div_scale_f32 v33, vcc, v22, v26, v22
	v_mul_f32_e32 v34, v33, v31
	v_fma_f32 v37, -v27, v34, v33
	v_fmac_f32_e32 v34, v37, v31
	v_fma_f32 v27, -v27, v34, v33
	v_div_fmas_f32 v27, v27, v31, v34
	v_div_fixup_f32 v22, v27, v26, v22
	v_mul_f32_e32 v26, 0xbfb8aa3b, v23
	v_exp_f32_e32 v26, v26
	s_nop 0
	v_add_f32_e32 v26, 1.0, v26
	v_div_scale_f32 v27, s[0:1], v26, v26, v23
	v_rcp_f32_e32 v31, v27
	s_nop 0
	v_fma_f32 v33, -v27, v31, 1.0
	v_fmac_f32_e32 v31, v33, v31
	v_div_scale_f32 v33, vcc, v23, v26, v23
	v_mul_f32_e32 v34, v33, v31
	v_fma_f32 v37, -v27, v34, v33
	v_fmac_f32_e32 v34, v37, v31
	v_fma_f32 v27, -v27, v34, v33
	v_div_fmas_f32 v27, v27, v31, v34
	v_div_fixup_f32 v23, v27, v26, v23
	v_cvt_pk_bf16_f32 v22, v22, v23
	v_add_u32_e32 v23, 14, v19
	v_cmp_lt_i32_e32 vcc, -15, v19
	v_cmp_gt_u32_e64 s[0:1], s14, v23
	ds_write_b16 v21, v22 offset:22
	ds_write_b16_d16_hi v18, v22 offset:22
	s_and_b64 s[18:19], vcc, s[0:1]
	v_mov_b32_e32 v22, 0
	v_mov_b32_e32 v26, 0
	s_and_saveexec_b64 s[0:1], s[18:19]
	s_cbranch_execz .LBB0_498
	v_mad_u64_u32 v[26:27], s[18:19], v23, s50, v[16:17]
	v_mov_b32_e32 v26, v143
; #define LAS __attribute__((address_space(3)))
; __device__ __forceinline__ unsigned pk2(float lo, float hi) { unsigned r; asm volatile("v_cvt_pk_bf16_f32 %0, %1, %2" : "=v"(r) : "v"(lo), "v"(hi)); return r; }
; __device__ __forceinline__ float lo16(unsigned w) { return __uint_as_float(w << 16); }
; __device__ __forceinline__ float hi16(unsigned w) { return __uint_as_float(w & 0xffff0000u); }
; __device__ __forceinline__ float siluf_(float x) { return x / (1.0f + __expf(-x)); }
; template <class Put>
; __device__ __forceinline__ void conv_pair32(const bf16* Pseq  , int L, int p0, int xch, const float* cw, const float* cb, const Put& put) {
;     ...
;     for (int i = 0; i < 36; ++i) {
;         const int pos = p0 + i - 2;
;         unsigned raw = 0u;
;         if (pos >= 0 && pos < L) raw = *(const unsigned*)(Pseq + (size_t)pos * LDP + xch);
;         a0 = a1; a1 = a2; a2 = a3; a3 = a4; a4 = lo16(raw);
;         c0 = c1; c1 = c2; c2 = c3; c3 = c4; c4 = hi16(raw);
;         if (i >= 4) {
;             const float v0 = b0 + w0[0] * a0 + w0[1] * a1 + w0[2] * a2 + w0[3] * a3 + w0[4] * a4;
;             const float v1 = b1 + w1[0] * c0 + w1[1] * c1 + w1[2] * c2 + w1[3] * c3 + w1[4] * c4;
;             put(i - 4, siluf_(v0), siluf_(v1));
;         }
; __device__ __forceinline__ void ssd_state_unit(const Params& p, int layer, LAS unsigned char* lds, int b, int cc, int g) {
;     ...
;         conv_pair32(Pm + (size_t)G.Rseq0 * LDP + C_BX, G.L, G.pos0 + q * 32, xch, cw, cb, [&](int l, float v0, float v1) {
;             const unsigned pk = pk2(v0, v1); const int ll = q * 32 + l;
;             *(LAS unsigned short*)(dst + ll * 2) = (unsigned short)(pk & 0xffffu); *(LAS unsigned short*)(dst + pitch + ll * 2) = (unsigned short)(pk >> 16); });
.LBB0_498:
	s_or_b64 exec, exec, s[0:1]
	v_fma_f32 v23, v10, v35, v4
	v_fmac_f32_e32 v23, v12, v36
	v_fmac_f32_e32 v23, v6, v32
	s_waitcnt vmcnt(0)
	v_lshlrev_b32_e32 v31, 16, v26
	v_fmac_f32_e32 v23, v8, v30
	v_fmac_f32_e32 v23, v14, v31
	v_fma_f32 v27, v11, v28, v5
	v_mul_f32_e32 v28, 0xbfb8aa3b, v23
	v_exp_f32_e32 v28, v28
	v_fmac_f32_e32 v27, v13, v29
	v_fmac_f32_e32 v27, v7, v24
	v_and_b32_e32 v26, 0xffff0000, v26
	v_add_f32_e32 v28, 1.0, v28
	v_div_scale_f32 v33, s[0:1], v28, v28, v23
	v_rcp_f32_e32 v34, v33
	v_fmac_f32_e32 v27, v9, v25
	v_fmac_f32_e32 v27, v15, v26
	v_fma_f32 v35, -v33, v34, 1.0
	v_fmac_f32_e32 v34, v35, v34
	v_div_scale_f32 v35, vcc, v23, v28, v23
	v_mul_f32_e32 v37, v35, v34
	v_fma_f32 v38, -v33, v37, v35
	v_fmac_f32_e32 v37, v38, v34
	v_fma_f32 v33, -v33, v37, v35
	v_div_fmas_f32 v33, v33, v34, v37
	v_div_fixup_f32 v23, v33, v28, v23
	v_mul_f32_e32 v28, 0xbfb8aa3b, v27
	v_exp_f32_e32 v28, v28
	s_nop 0
	v_add_f32_e32 v28, 1.0, v28
	v_div_scale_f32 v33, s[0:1], v28, v28, v27
	v_rcp_f32_e32 v34, v33
	s_nop 0
	v_fma_f32 v35, -v33, v34, 1.0
	v_fmac_f32_e32 v34, v35, v34
	v_div_scale_f32 v35, vcc, v27, v28, v27
	v_mul_f32_e32 v37, v35, v34
	v_fma_f32 v38, -v33, v37, v35
	v_fmac_f32_e32 v37, v38, v34
	v_fma_f32 v33, -v33, v37, v35
	v_div_fmas_f32 v33, v33, v34, v37
	v_div_fixup_f32 v27, v33, v28, v27
	v_cvt_pk_bf16_f32 v23, v23, v27
	ds_write_b16 v21, v23 offset:24
	ds_write_b16_d16_hi v18, v23 offset:24
	v_add_u32_e32 v23, 15, v19
	v_cmp_lt_i32_e32 vcc, -16, v19
	v_cmp_gt_u32_e64 s[0:1], s14, v23
	s_and_b64 s[18:19], vcc, s[0:1]
	s_and_saveexec_b64 s[0:1], s[18:19]
	s_cbranch_execz .LBB0_500
	v_mad_u64_u32 v[22:23], s[18:19], v23, s50, v[16:17]
	v_mov_b32_e32 v22, v144
.LBB0_500:
	s_or_b64 exec, exec, s[0:1]
	v_fma_f32 v23, v10, v36, v4
	v_fmac_f32_e32 v23, v12, v32
	v_fmac_f32_e32 v23, v6, v30
	s_waitcnt vmcnt(0)
	v_lshlrev_b32_e32 v27, 16, v22
	v_fmac_f32_e32 v23, v8, v31
	v_fmac_f32_e32 v23, v14, v27
	v_fma_f32 v28, v11, v29, v5
	v_mul_f32_e32 v29, 0xbfb8aa3b, v23
	v_exp_f32_e32 v29, v29
	v_fmac_f32_e32 v28, v13, v24
	v_fmac_f32_e32 v28, v7, v25
	v_and_b32_e32 v22, 0xffff0000, v22
	v_add_f32_e32 v29, 1.0, v29
	v_div_scale_f32 v33, s[0:1], v29, v29, v23
	v_rcp_f32_e32 v34, v33
	v_fmac_f32_e32 v28, v9, v26
	v_fmac_f32_e32 v28, v15, v22
	v_fma_f32 v35, -v33, v34, 1.0
	v_fmac_f32_e32 v34, v35, v34
	v_div_scale_f32 v35, vcc, v23, v29, v23
	v_mul_f32_e32 v36, v35, v34
	v_fma_f32 v37, -v33, v36, v35
	v_fmac_f32_e32 v36, v37, v34
	v_fma_f32 v33, -v33, v36, v35
	v_div_fmas_f32 v33, v33, v34, v36
	v_div_fixup_f32 v23, v33, v29, v23
	v_mul_f32_e32 v29, 0xbfb8aa3b, v28
	v_exp_f32_e32 v29, v29
	s_nop 0
	v_add_f32_e32 v29, 1.0, v29
	v_div_scale_f32 v33, s[0:1], v29, v29, v28
	v_rcp_f32_e32 v34, v33
	s_movk_i32 s0, 0xffef
	v_fma_f32 v35, -v33, v34, 1.0
	v_fmac_f32_e32 v34, v35, v34
	v_div_scale_f32 v35, vcc, v28, v29, v28
	v_mul_f32_e32 v36, v35, v34
	v_fma_f32 v37, -v33, v36, v35
	v_fmac_f32_e32 v36, v37, v34
	v_fma_f32 v33, -v33, v36, v35
	v_div_fmas_f32 v33, v33, v34, v36
	v_div_fixup_f32 v28, v33, v29, v28
	v_cvt_pk_bf16_f32 v23, v23, v28
	ds_write_b16 v21, v23 offset:26
	ds_write_b16_d16_hi v18, v23 offset:26
	v_add_u32_e32 v23, 16, v19
	v_cmp_lt_i32_e32 vcc, s0, v19
	v_cmp_gt_u32_e64 s[0:1], s14, v23
	s_and_b64 s[18:19], vcc, s[0:1]
	v_mov_b32_e32 v33, 0
	v_mov_b32_e32 v29, 0
	s_and_saveexec_b64 s[0:1], s[18:19]
	s_cbranch_execz .LBB0_502
	v_mad_u64_u32 v[28:29], s[18:19], v23, s50, v[16:17]
	v_mov_b32_e32 v29, v145
.LBB0_502:
	s_or_b64 exec, exec, s[0:1]
	s_waitcnt vmcnt(0)
	v_lshlrev_b32_e32 v28, 16, v29
	v_and_b32_e32 v23, 0xffff0000, v29
	v_fma_f32 v29, v10, v32, v4
	v_fmac_f32_e32 v29, v12, v30
	v_fmac_f32_e32 v29, v6, v31
	v_fmac_f32_e32 v29, v8, v27
	v_fmac_f32_e32 v29, v14, v28
	v_mul_f32_e32 v32, 0xbfb8aa3b, v29
	v_exp_f32_e32 v32, v32
	v_fma_f32 v24, v11, v24, v5
	v_fmac_f32_e32 v24, v13, v25
	v_fmac_f32_e32 v24, v7, v26
	v_add_f32_e32 v32, 1.0, v32
	v_div_scale_f32 v34, s[0:1], v32, v32, v29
	v_rcp_f32_e32 v35, v34
	v_fmac_f32_e32 v24, v9, v22
	v_fmac_f32_e32 v24, v15, v23
	v_fma_f32 v36, -v34, v35, 1.0
	v_fmac_f32_e32 v35, v36, v35
	v_div_scale_f32 v36, vcc, v29, v32, v29
	v_mul_f32_e32 v37, v36, v35
	v_fma_f32 v38, -v34, v37, v36
	v_fmac_f32_e32 v37, v38, v35
	v_fma_f32 v34, -v34, v37, v36
	v_div_fmas_f32 v34, v34, v35, v37
	v_div_fixup_f32 v29, v34, v32, v29
	v_mul_f32_e32 v32, 0xbfb8aa3b, v24
	v_exp_f32_e32 v32, v32
	s_nop 0
	v_add_f32_e32 v32, 1.0, v32
	v_div_scale_f32 v34, s[0:1], v32, v32, v24
	v_rcp_f32_e32 v35, v34
	s_movk_i32 s0, 0xffee
	v_fma_f32 v36, -v34, v35, 1.0
	v_fmac_f32_e32 v35, v36, v35
	v_div_scale_f32 v36, vcc, v24, v32, v24
	v_mul_f32_e32 v37, v36, v35
	v_fma_f32 v38, -v34, v37, v36
	v_fmac_f32_e32 v37, v38, v35
	v_fma_f32 v34, -v34, v37, v36
	v_div_fmas_f32 v34, v34, v35, v37
	v_div_fixup_f32 v24, v34, v32, v24
	v_cvt_pk_bf16_f32 v24, v29, v24
	ds_write_b16 v21, v24 offset:28
	ds_write_b16_d16_hi v18, v24 offset:28
	v_add_u32_e32 v24, 17, v19
	v_cmp_lt_i32_e32 vcc, s0, v19
	v_cmp_gt_u32_e64 s[0:1], s14, v24
	s_and_b64 s[18:19], vcc, s[0:1]
	s_and_saveexec_b64 s[0:1], s[18:19]
	s_cbranch_execz .LBB0_504
	v_mad_u64_u32 v[32:33], s[18:19], v24, s50, v[16:17]
	v_mov_b32_e32 v33, v146
; #define LAS __attribute__((address_space(3)))
; __device__ __forceinline__ unsigned pk2(float lo, float hi) { unsigned r; asm volatile("v_cvt_pk_bf16_f32 %0, %1, %2" : "=v"(r) : "v"(lo), "v"(hi)); return r; }
; __device__ __forceinline__ float lo16(unsigned w) { return __uint_as_float(w << 16); }
; __device__ __forceinline__ float hi16(unsigned w) { return __uint_as_float(w & 0xffff0000u); }
; __device__ __forceinline__ float siluf_(float x) { return x / (1.0f + __expf(-x)); }
; template <class Put>
; __device__ __forceinline__ void conv_pair32(const bf16* Pseq  , int L, int p0, int xch, const float* cw, const float* cb, const Put& put) {
;     ...
;     for (int i = 0; i < 36; ++i) {
;         const int pos = p0 + i - 2;
;         unsigned raw = 0u;
;         if (pos >= 0 && pos < L) raw = *(const unsigned*)(Pseq + (size_t)pos * LDP + xch);
;         a0 = a1; a1 = a2; a2 = a3; a3 = a4; a4 = lo16(raw);
;         c0 = c1; c1 = c2; c2 = c3; c3 = c4; c4 = hi16(raw);
;         if (i >= 4) {
;             const float v0 = b0 + w0[0] * a0 + w0[1] * a1 + w0[2] * a2 + w0[3] * a3 + w0[4] * a4;
;             const float v1 = b1 + w1[0] * c0 + w1[1] * c1 + w1[2] * c2 + w1[3] * c3 + w1[4] * c4;
;             put(i - 4, siluf_(v0), siluf_(v1));
;         }
; __device__ __forceinline__ void ssd_state_unit(const Params& p, int layer, LAS unsigned char* lds, int b, int cc, int g) {
;     ...
;         conv_pair32(Pm + (size_t)G.Rseq0 * LDP + C_BX, G.L, G.pos0 + q * 32, xch, cw, cb, [&](int l, float v0, float v1) {
;             const unsigned pk = pk2(v0, v1); const int ll = q * 32 + l;
;             *(LAS unsigned short*)(dst + ll * 2) = (unsigned short)(pk & 0xffffu); *(LAS unsigned short*)(dst + pitch + ll * 2) = (unsigned short)(pk >> 16); });
.LBB0_504:
	s_or_b64 exec, exec, s[0:1]
	v_fma_f32 v30, v10, v30, v4
	v_fmac_f32_e32 v30, v12, v31
	v_fmac_f32_e32 v30, v6, v27
	s_waitcnt vmcnt(0)
	v_lshlrev_b32_e32 v29, 16, v33
	v_fmac_f32_e32 v30, v8, v28
	v_fmac_f32_e32 v30, v14, v29
	v_mul_f32_e32 v32, 0xbfb8aa3b, v30
	v_exp_f32_e32 v32, v32
	v_and_b32_e32 v24, 0xffff0000, v33
	v_fma_f32 v25, v11, v25, v5
	v_fmac_f32_e32 v25, v13, v26
	v_add_f32_e32 v32, 1.0, v32
	v_div_scale_f32 v33, s[0:1], v32, v32, v30
	v_rcp_f32_e32 v34, v33
	v_fmac_f32_e32 v25, v7, v22
	v_fmac_f32_e32 v25, v9, v23
	v_fmac_f32_e32 v25, v15, v24
	v_fma_f32 v35, -v33, v34, 1.0
	v_fmac_f32_e32 v34, v35, v34
	v_div_scale_f32 v35, vcc, v30, v32, v30
	v_mul_f32_e32 v36, v35, v34
	v_fma_f32 v37, -v33, v36, v35
	v_fmac_f32_e32 v36, v37, v34
	v_fma_f32 v33, -v33, v36, v35
	v_div_fmas_f32 v33, v33, v34, v36
	v_div_fixup_f32 v30, v33, v32, v30
	v_mul_f32_e32 v32, 0xbfb8aa3b, v25
	v_exp_f32_e32 v32, v32
	s_nop 0
	v_add_f32_e32 v32, 1.0, v32
	v_div_scale_f32 v33, s[0:1], v32, v32, v25
	v_rcp_f32_e32 v34, v33
	s_movk_i32 s0, 0xffed
	v_fma_f32 v35, -v33, v34, 1.0
	v_fmac_f32_e32 v34, v35, v34
	v_div_scale_f32 v35, vcc, v25, v32, v25
	v_mul_f32_e32 v36, v35, v34
	v_fma_f32 v37, -v33, v36, v35
	v_fmac_f32_e32 v36, v37, v34
	v_fma_f32 v33, -v33, v36, v35
	v_div_fmas_f32 v33, v33, v34, v36
	v_div_fixup_f32 v25, v33, v32, v25
	v_cvt_pk_bf16_f32 v25, v30, v25
	ds_write_b16 v21, v25 offset:30
	ds_write_b16_d16_hi v18, v25 offset:30
	v_add_u32_e32 v25, 18, v19
	v_cmp_lt_i32_e32 vcc, s0, v19
	v_cmp_gt_u32_e64 s[0:1], s14, v25
	s_and_b64 s[18:19], vcc, s[0:1]
	v_mov_b32_e32 v32, 0
	v_mov_b32_e32 v33, 0
	s_and_saveexec_b64 s[0:1], s[18:19]
	s_cbranch_execz .LBB0_506
	v_mad_u64_u32 v[34:35], s[18:19], v25, s50, v[16:17]
	v_mov_b32_e32 v33, v147
.LBB0_506:
	s_or_b64 exec, exec, s[0:1]
	v_fma_f32 v31, v10, v31, v4
	v_fmac_f32_e32 v31, v12, v27
	v_fmac_f32_e32 v31, v6, v28
	s_waitcnt vmcnt(0)
	v_lshlrev_b32_e32 v30, 16, v33
	v_fmac_f32_e32 v31, v8, v29
	v_fmac_f32_e32 v31, v14, v30
	v_and_b32_e32 v25, 0xffff0000, v33
	v_mul_f32_e32 v33, 0xbfb8aa3b, v31
	v_exp_f32_e32 v33, v33
	v_fma_f32 v26, v11, v26, v5
	v_fmac_f32_e32 v26, v13, v22
	v_fmac_f32_e32 v26, v7, v23
	v_add_f32_e32 v33, 1.0, v33
	v_div_scale_f32 v34, s[0:1], v33, v33, v31
	v_rcp_f32_e32 v35, v34
	v_fmac_f32_e32 v26, v9, v24
	v_fmac_f32_e32 v26, v15, v25
	v_fma_f32 v36, -v34, v35, 1.0
	v_fmac_f32_e32 v35, v36, v35
	v_div_scale_f32 v36, vcc, v31, v33, v31
	v_mul_f32_e32 v37, v36, v35
	v_fma_f32 v38, -v34, v37, v36
	v_fmac_f32_e32 v37, v38, v35
	v_fma_f32 v34, -v34, v37, v36
	v_div_fmas_f32 v34, v34, v35, v37
	v_div_fixup_f32 v31, v34, v33, v31
	v_mul_f32_e32 v33, 0xbfb8aa3b, v26
	v_exp_f32_e32 v33, v33
	s_nop 0
	v_add_f32_e32 v33, 1.0, v33
	v_div_scale_f32 v34, s[0:1], v33, v33, v26
	v_rcp_f32_e32 v35, v34
	s_movk_i32 s0, 0xffec
	v_fma_f32 v36, -v34, v35, 1.0
	v_fmac_f32_e32 v35, v36, v35
	v_div_scale_f32 v36, vcc, v26, v33, v26
	v_mul_f32_e32 v37, v36, v35
	v_fma_f32 v38, -v34, v37, v36
	v_fmac_f32_e32 v37, v38, v35
	v_fma_f32 v34, -v34, v37, v36
	v_div_fmas_f32 v34, v34, v35, v37
	v_div_fixup_f32 v26, v34, v33, v26
	v_cvt_pk_bf16_f32 v26, v31, v26
	ds_write_b16 v21, v26 offset:32
	ds_write_b16_d16_hi v18, v26 offset:32
	v_add_u32_e32 v26, 19, v19
	v_cmp_lt_i32_e32 vcc, s0, v19
	v_cmp_gt_u32_e64 s[0:1], s14, v26
	s_and_b64 s[18:19], vcc, s[0:1]
	s_and_saveexec_b64 s[0:1], s[18:19]
	s_cbranch_execz .LBB0_508
	v_mad_u64_u32 v[32:33], s[18:19], v26, s50, v[16:17]
	v_mov_b32_e32 v32, v148
.LBB0_508:
	s_or_b64 exec, exec, s[0:1]
	v_fma_f32 v27, v10, v27, v4
	v_fmac_f32_e32 v27, v12, v28
	v_fmac_f32_e32 v27, v6, v29
	s_waitcnt vmcnt(0)
	v_lshlrev_b32_e32 v31, 16, v32
	v_fmac_f32_e32 v27, v8, v30
	v_fmac_f32_e32 v27, v14, v31
	v_and_b32_e32 v26, 0xffff0000, v32
	v_mul_f32_e32 v32, 0xbfb8aa3b, v27
	v_exp_f32_e32 v32, v32
	v_fma_f32 v22, v11, v22, v5
	v_fmac_f32_e32 v22, v13, v23
	v_fmac_f32_e32 v22, v7, v24
	v_add_f32_e32 v32, 1.0, v32
	v_div_scale_f32 v33, s[0:1], v32, v32, v27
	v_rcp_f32_e32 v34, v33
	v_fmac_f32_e32 v22, v9, v25
	v_fmac_f32_e32 v22, v15, v26
	v_fma_f32 v35, -v33, v34, 1.0
	v_fmac_f32_e32 v34, v35, v34
	v_div_scale_f32 v35, vcc, v27, v32, v27
	v_mul_f32_e32 v36, v35, v34
	v_fma_f32 v37, -v33, v36, v35
	v_fmac_f32_e32 v36, v37, v34
	v_fma_f32 v33, -v33, v36, v35
	v_div_fmas_f32 v33, v33, v34, v36
	v_div_fixup_f32 v27, v33, v32, v27
	v_mul_f32_e32 v32, 0xbfb8aa3b, v22
	v_exp_f32_e32 v32, v32
	s_nop 0
	v_add_f32_e32 v32, 1.0, v32
	v_div_scale_f32 v33, s[0:1], v32, v32, v22
	v_rcp_f32_e32 v34, v33
	s_movk_i32 s0, 0xffeb
	v_fma_f32 v35, -v33, v34, 1.0
	v_fmac_f32_e32 v34, v35, v34
	v_div_scale_f32 v35, vcc, v22, v32, v22
	v_mul_f32_e32 v36, v35, v34
	v_fma_f32 v37, -v33, v36, v35
	v_fmac_f32_e32 v36, v37, v34
	v_fma_f32 v33, -v33, v36, v35
	v_div_fmas_f32 v33, v33, v34, v36
	v_div_fixup_f32 v22, v33, v32, v22
	v_cvt_pk_bf16_f32 v22, v27, v22
	ds_write_b16 v21, v22 offset:34
	ds_write_b16_d16_hi v18, v22 offset:34
	v_add_u32_e32 v22, 20, v19
	v_cmp_lt_i32_e32 vcc, s0, v19
	v_cmp_gt_u32_e64 s[0:1], s14, v22
	s_and_b64 s[18:19], vcc, s[0:1]
	v_mov_b32_e32 v32, 0
	v_mov_b32_e32 v33, 0
	s_and_saveexec_b64 s[0:1], s[18:19]
	s_cbranch_execz .LBB0_510
	v_mad_u64_u32 v[34:35], s[18:19], v22, s50, v[16:17]
	v_mov_b32_e32 v33, v149
; #define LAS __attribute__((address_space(3)))
; __device__ __forceinline__ unsigned pk2(float lo, float hi) { unsigned r; asm volatile("v_cvt_pk_bf16_f32 %0, %1, %2" : "=v"(r) : "v"(lo), "v"(hi)); return r; }
; __device__ __forceinline__ float lo16(unsigned w) { return __uint_as_float(w << 16); }
; __device__ __forceinline__ float hi16(unsigned w) { return __uint_as_float(w & 0xffff0000u); }
; __device__ __forceinline__ float siluf_(float x) { return x / (1.0f + __expf(-x)); }
; template <class Put>
; __device__ __forceinline__ void conv_pair32(const bf16* Pseq  , int L, int p0, int xch, const float* cw, const float* cb, const Put& put) {
;     ...
;     for (int i = 0; i < 36; ++i) {
;         const int pos = p0 + i - 2;
;         unsigned raw = 0u;
;         if (pos >= 0 && pos < L) raw = *(const unsigned*)(Pseq + (size_t)pos * LDP + xch);
;         a0 = a1; a1 = a2; a2 = a3; a3 = a4; a4 = lo16(raw);
;         c0 = c1; c1 = c2; c2 = c3; c3 = c4; c4 = hi16(raw);
;         if (i >= 4) {
;             const float v0 = b0 + w0[0] * a0 + w0[1] * a1 + w0[2] * a2 + w0[3] * a3 + w0[4] * a4;
;             const float v1 = b1 + w1[0] * c0 + w1[1] * c1 + w1[2] * c2 + w1[3] * c3 + w1[4] * c4;
;             put(i - 4, siluf_(v0), siluf_(v1));
;         }
; __device__ __forceinline__ void ssd_state_unit(const Params& p, int layer, LAS unsigned char* lds, int b, int cc, int g) {
;     ...
;         conv_pair32(Pm + (size_t)G.Rseq0 * LDP + C_BX, G.L, G.pos0 + q * 32, xch, cw, cb, [&](int l, float v0, float v1) {
;             const unsigned pk = pk2(v0, v1); const int ll = q * 32 + l;
;             *(LAS unsigned short*)(dst + ll * 2) = (unsigned short)(pk & 0xffffu); *(LAS unsigned short*)(dst + pitch + ll * 2) = (unsigned short)(pk >> 16); });
.LBB0_510:
	s_or_b64 exec, exec, s[0:1]
	v_fma_f32 v28, v10, v28, v4
	v_fmac_f32_e32 v28, v12, v29
	v_fmac_f32_e32 v28, v6, v30
	s_waitcnt vmcnt(0)
	v_lshlrev_b32_e32 v27, 16, v33
	v_fmac_f32_e32 v28, v8, v31
	v_fmac_f32_e32 v28, v14, v27
	v_and_b32_e32 v22, 0xffff0000, v33
	v_mul_f32_e32 v33, 0xbfb8aa3b, v28
	v_exp_f32_e32 v33, v33
	v_fma_f32 v23, v11, v23, v5
	v_fmac_f32_e32 v23, v13, v24
	v_fmac_f32_e32 v23, v7, v25
	v_add_f32_e32 v33, 1.0, v33
	v_div_scale_f32 v34, s[0:1], v33, v33, v28
	v_rcp_f32_e32 v35, v34
	v_fmac_f32_e32 v23, v9, v26
	v_fmac_f32_e32 v23, v15, v22
	v_fma_f32 v36, -v34, v35, 1.0
	v_fmac_f32_e32 v35, v36, v35
	v_div_scale_f32 v36, vcc, v28, v33, v28
	v_mul_f32_e32 v37, v36, v35
	v_fma_f32 v38, -v34, v37, v36
	v_fmac_f32_e32 v37, v38, v35
	v_fma_f32 v34, -v34, v37, v36
	v_div_fmas_f32 v34, v34, v35, v37
	v_div_fixup_f32 v28, v34, v33, v28
	v_mul_f32_e32 v33, 0xbfb8aa3b, v23
	v_exp_f32_e32 v33, v33
	s_nop 0
	v_add_f32_e32 v33, 1.0, v33
	v_div_scale_f32 v34, s[0:1], v33, v33, v23
	v_rcp_f32_e32 v35, v34
	s_movk_i32 s0, 0xffea
	v_fma_f32 v36, -v34, v35, 1.0
	v_fmac_f32_e32 v35, v36, v35
	v_div_scale_f32 v36, vcc, v23, v33, v23
	v_mul_f32_e32 v37, v36, v35
	v_fma_f32 v38, -v34, v37, v36
	v_fmac_f32_e32 v37, v38, v35
	v_fma_f32 v34, -v34, v37, v36
	v_div_fmas_f32 v34, v34, v35, v37
	v_div_fixup_f32 v23, v34, v33, v23
	v_cvt_pk_bf16_f32 v23, v28, v23
	ds_write_b16 v21, v23 offset:36
	ds_write_b16_d16_hi v18, v23 offset:36
	v_add_u32_e32 v23, 21, v19
	v_cmp_lt_i32_e32 vcc, s0, v19
	v_cmp_gt_u32_e64 s[0:1], s14, v23
	s_and_b64 s[18:19], vcc, s[0:1]
	s_and_saveexec_b64 s[0:1], s[18:19]
	s_cbranch_execz .LBB0_512
	v_mad_u64_u32 v[32:33], s[18:19], v23, s50, v[16:17]
	v_mov_b32_e32 v32, v150
.LBB0_512:
	s_or_b64 exec, exec, s[0:1]
	v_fma_f32 v29, v10, v29, v4
	v_fmac_f32_e32 v29, v12, v30
	v_fmac_f32_e32 v29, v6, v31
	s_waitcnt vmcnt(0)
	v_lshlrev_b32_e32 v28, 16, v32
	v_fmac_f32_e32 v29, v8, v27
	v_fmac_f32_e32 v29, v14, v28
	v_and_b32_e32 v23, 0xffff0000, v32
	v_mul_f32_e32 v32, 0xbfb8aa3b, v29
	v_exp_f32_e32 v32, v32
	v_fma_f32 v24, v11, v24, v5
	v_fmac_f32_e32 v24, v13, v25
	v_fmac_f32_e32 v24, v7, v26
	v_add_f32_e32 v32, 1.0, v32
	v_div_scale_f32 v33, s[0:1], v32, v32, v29
	v_rcp_f32_e32 v34, v33
	v_fmac_f32_e32 v24, v9, v22
	v_fmac_f32_e32 v24, v15, v23
	v_fma_f32 v35, -v33, v34, 1.0
	v_fmac_f32_e32 v34, v35, v34
	v_div_scale_f32 v35, vcc, v29, v32, v29
	v_mul_f32_e32 v36, v35, v34
	v_fma_f32 v37, -v33, v36, v35
	v_fmac_f32_e32 v36, v37, v34
	v_fma_f32 v33, -v33, v36, v35
	v_div_fmas_f32 v33, v33, v34, v36
	v_div_fixup_f32 v29, v33, v32, v29
	v_mul_f32_e32 v32, 0xbfb8aa3b, v24
	v_exp_f32_e32 v32, v32
	s_nop 0
	v_add_f32_e32 v32, 1.0, v32
	v_div_scale_f32 v33, s[0:1], v32, v32, v24
	v_rcp_f32_e32 v34, v33
	s_movk_i32 s0, 0xffe9
	v_fma_f32 v35, -v33, v34, 1.0
	v_fmac_f32_e32 v34, v35, v34
	v_div_scale_f32 v35, vcc, v24, v32, v24
	v_mul_f32_e32 v36, v35, v34
	v_fma_f32 v37, -v33, v36, v35
	v_fmac_f32_e32 v36, v37, v34
	v_fma_f32 v33, -v33, v36, v35
	v_div_fmas_f32 v33, v33, v34, v36
	v_div_fixup_f32 v24, v33, v32, v24
	v_cvt_pk_bf16_f32 v24, v29, v24
	ds_write_b16 v21, v24 offset:38
	ds_write_b16_d16_hi v18, v24 offset:38
	v_add_u32_e32 v24, 22, v19
	v_cmp_lt_i32_e32 vcc, s0, v19
	v_cmp_gt_u32_e64 s[0:1], s14, v24
	s_and_b64 s[18:19], vcc, s[0:1]
	v_mov_b32_e32 v32, 0
	v_mov_b32_e32 v33, 0
	s_and_saveexec_b64 s[0:1], s[18:19]
	s_cbranch_execz .LBB0_514
	v_mad_u64_u32 v[34:35], s[18:19], v24, s50, v[16:17]
	v_mov_b32_e32 v33, v151
.LBB0_514:
	s_or_b64 exec, exec, s[0:1]
	v_fma_f32 v30, v10, v30, v4
	v_fmac_f32_e32 v30, v12, v31
	v_fmac_f32_e32 v30, v6, v27
	s_waitcnt vmcnt(0)
	v_lshlrev_b32_e32 v29, 16, v33
	v_fmac_f32_e32 v30, v8, v28
	v_fmac_f32_e32 v30, v14, v29
	v_and_b32_e32 v24, 0xffff0000, v33
	v_mul_f32_e32 v33, 0xbfb8aa3b, v30
	v_exp_f32_e32 v33, v33
	v_fma_f32 v25, v11, v25, v5
	v_fmac_f32_e32 v25, v13, v26
	v_fmac_f32_e32 v25, v7, v22
	v_add_f32_e32 v33, 1.0, v33
	v_div_scale_f32 v34, s[0:1], v33, v33, v30
	v_rcp_f32_e32 v35, v34
	v_fmac_f32_e32 v25, v9, v23
	v_fmac_f32_e32 v25, v15, v24
	v_fma_f32 v36, -v34, v35, 1.0
	v_fmac_f32_e32 v35, v36, v35
	v_div_scale_f32 v36, vcc, v30, v33, v30
	v_mul_f32_e32 v37, v36, v35
	v_fma_f32 v38, -v34, v37, v36
	v_fmac_f32_e32 v37, v38, v35
	v_fma_f32 v34, -v34, v37, v36
	v_div_fmas_f32 v34, v34, v35, v37
	v_div_fixup_f32 v30, v34, v33, v30
	v_mul_f32_e32 v33, 0xbfb8aa3b, v25
	v_exp_f32_e32 v33, v33
	s_nop 0
	v_add_f32_e32 v33, 1.0, v33
	v_div_scale_f32 v34, s[0:1], v33, v33, v25
	v_rcp_f32_e32 v35, v34
	s_movk_i32 s0, 0xffe8
	v_fma_f32 v36, -v34, v35, 1.0
	v_fmac_f32_e32 v35, v36, v35
	v_div_scale_f32 v36, vcc, v25, v33, v25
	v_mul_f32_e32 v37, v36, v35
	v_fma_f32 v38, -v34, v37, v36
	v_fmac_f32_e32 v37, v38, v35
	v_fma_f32 v34, -v34, v37, v36
	v_div_fmas_f32 v34, v34, v35, v37
	v_div_fixup_f32 v25, v34, v33, v25
	v_cvt_pk_bf16_f32 v25, v30, v25
	ds_write_b16 v21, v25 offset:40
	ds_write_b16_d16_hi v18, v25 offset:40
	v_add_u32_e32 v25, 23, v19
	v_cmp_lt_i32_e32 vcc, s0, v19
	v_cmp_gt_u32_e64 s[0:1], s14, v25
	s_and_b64 s[18:19], vcc, s[0:1]
	s_and_saveexec_b64 s[0:1], s[18:19]
	s_cbranch_execz .LBB0_516
	v_mad_u64_u32 v[32:33], s[18:19], v25, s50, v[16:17]
	v_mov_b32_e32 v32, v152
; #define LAS __attribute__((address_space(3)))
; __device__ __forceinline__ unsigned pk2(float lo, float hi) { unsigned r; asm volatile("v_cvt_pk_bf16_f32 %0, %1, %2" : "=v"(r) : "v"(lo), "v"(hi)); return r; }
; __device__ __forceinline__ float lo16(unsigned w) { return __uint_as_float(w << 16); }
; __device__ __forceinline__ float hi16(unsigned w) { return __uint_as_float(w & 0xffff0000u); }
; __device__ __forceinline__ float siluf_(float x) { return x / (1.0f + __expf(-x)); }
; template <class Put>
; __device__ __forceinline__ void conv_pair32(const bf16* Pseq  , int L, int p0, int xch, const float* cw, const float* cb, const Put& put) {
;     ...
;     for (int i = 0; i < 36; ++i) {
;         const int pos = p0 + i - 2;
;         unsigned raw = 0u;
;         if (pos >= 0 && pos < L) raw = *(const unsigned*)(Pseq + (size_t)pos * LDP + xch);
;         a0 = a1; a1 = a2; a2 = a3; a3 = a4; a4 = lo16(raw);
;         c0 = c1; c1 = c2; c2 = c3; c3 = c4; c4 = hi16(raw);
;         if (i >= 4) {
;             const float v0 = b0 + w0[0] * a0 + w0[1] * a1 + w0[2] * a2 + w0[3] * a3 + w0[4] * a4;
;             const float v1 = b1 + w1[0] * c0 + w1[1] * c1 + w1[2] * c2 + w1[3] * c3 + w1[4] * c4;
;             put(i - 4, siluf_(v0), siluf_(v1));
;         }
; __device__ __forceinline__ void ssd_state_unit(const Params& p, int layer, LAS unsigned char* lds, int b, int cc, int g) {
;     ...
;         conv_pair32(Pm + (size_t)G.Rseq0 * LDP + C_BX, G.L, G.pos0 + q * 32, xch, cw, cb, [&](int l, float v0, float v1) {
;             const unsigned pk = pk2(v0, v1); const int ll = q * 32 + l;
;             *(LAS unsigned short*)(dst + ll * 2) = (unsigned short)(pk & 0xffffu); *(LAS unsigned short*)(dst + pitch + ll * 2) = (unsigned short)(pk >> 16); });
.LBB0_516:
	s_or_b64 exec, exec, s[0:1]
	v_fma_f32 v31, v10, v31, v4
	v_fmac_f32_e32 v31, v12, v27
	v_fmac_f32_e32 v31, v6, v28
	s_waitcnt vmcnt(0)
	v_lshlrev_b32_e32 v30, 16, v32
	v_fmac_f32_e32 v31, v8, v29
	v_fmac_f32_e32 v31, v14, v30
	v_and_b32_e32 v25, 0xffff0000, v32
	v_mul_f32_e32 v32, 0xbfb8aa3b, v31
	v_exp_f32_e32 v32, v32
	v_fma_f32 v26, v11, v26, v5
	v_fmac_f32_e32 v26, v13, v22
	v_fmac_f32_e32 v26, v7, v23
	v_add_f32_e32 v32, 1.0, v32
	v_div_scale_f32 v33, s[0:1], v32, v32, v31
	v_rcp_f32_e32 v34, v33
	v_fmac_f32_e32 v26, v9, v24
	v_fmac_f32_e32 v26, v15, v25
	v_fma_f32 v35, -v33, v34, 1.0
	v_fmac_f32_e32 v34, v35, v34
	v_div_scale_f32 v35, vcc, v31, v32, v31
	v_mul_f32_e32 v36, v35, v34
	v_fma_f32 v37, -v33, v36, v35
	v_fmac_f32_e32 v36, v37, v34
	v_fma_f32 v33, -v33, v36, v35
	v_div_fmas_f32 v33, v33, v34, v36
	v_div_fixup_f32 v31, v33, v32, v31
	v_mul_f32_e32 v32, 0xbfb8aa3b, v26
	v_exp_f32_e32 v32, v32
	s_nop 0
	v_add_f32_e32 v32, 1.0, v32
	v_div_scale_f32 v33, s[0:1], v32, v32, v26
	v_rcp_f32_e32 v34, v33
	s_movk_i32 s0, 0xffe7
	v_fma_f32 v35, -v33, v34, 1.0
	v_fmac_f32_e32 v34, v35, v34
	v_div_scale_f32 v35, vcc, v26, v32, v26
	v_mul_f32_e32 v36, v35, v34
	v_fma_f32 v37, -v33, v36, v35
	v_fmac_f32_e32 v36, v37, v34
	v_fma_f32 v33, -v33, v36, v35
	v_div_fmas_f32 v33, v33, v34, v36
	v_div_fixup_f32 v26, v33, v32, v26
	v_cvt_pk_bf16_f32 v26, v31, v26
	ds_write_b16 v21, v26 offset:42
	ds_write_b16_d16_hi v18, v26 offset:42
	v_add_u32_e32 v26, 24, v19
	v_cmp_lt_i32_e32 vcc, s0, v19
	v_cmp_gt_u32_e64 s[0:1], s14, v26
	s_and_b64 s[18:19], vcc, s[0:1]
	v_mov_b32_e32 v32, 0
	v_mov_b32_e32 v33, 0
	s_and_saveexec_b64 s[0:1], s[18:19]
	s_cbranch_execz .LBB0_518
	v_mad_u64_u32 v[34:35], s[18:19], v26, s50, v[16:17]
	v_mov_b32_e32 v33, v153
.LBB0_518:
	s_or_b64 exec, exec, s[0:1]
	v_fma_f32 v27, v10, v27, v4
	v_fmac_f32_e32 v27, v12, v28
	v_fmac_f32_e32 v27, v6, v29
	s_waitcnt vmcnt(0)
	v_lshlrev_b32_e32 v31, 16, v33
	v_fmac_f32_e32 v27, v8, v30
	v_fmac_f32_e32 v27, v14, v31
	v_and_b32_e32 v26, 0xffff0000, v33
	v_mul_f32_e32 v33, 0xbfb8aa3b, v27
	v_exp_f32_e32 v33, v33
	v_fma_f32 v22, v11, v22, v5
	v_fmac_f32_e32 v22, v13, v23
	v_fmac_f32_e32 v22, v7, v24
	v_add_f32_e32 v33, 1.0, v33
	v_div_scale_f32 v34, s[0:1], v33, v33, v27
	v_rcp_f32_e32 v35, v34
	v_fmac_f32_e32 v22, v9, v25
	v_fmac_f32_e32 v22, v15, v26
	v_fma_f32 v36, -v34, v35, 1.0
	v_fmac_f32_e32 v35, v36, v35
	v_div_scale_f32 v36, vcc, v27, v33, v27
	v_mul_f32_e32 v37, v36, v35
	v_fma_f32 v38, -v34, v37, v36
	v_fmac_f32_e32 v37, v38, v35
	v_fma_f32 v34, -v34, v37, v36
	v_div_fmas_f32 v34, v34, v35, v37
	v_div_fixup_f32 v27, v34, v33, v27
	v_mul_f32_e32 v33, 0xbfb8aa3b, v22
	v_exp_f32_e32 v33, v33
	s_nop 0
	v_add_f32_e32 v33, 1.0, v33
	v_div_scale_f32 v34, s[0:1], v33, v33, v22
	v_rcp_f32_e32 v35, v34
	s_movk_i32 s0, 0xffe6
	v_fma_f32 v36, -v34, v35, 1.0
	v_fmac_f32_e32 v35, v36, v35
	v_div_scale_f32 v36, vcc, v22, v33, v22
	v_mul_f32_e32 v37, v36, v35
	v_fma_f32 v38, -v34, v37, v36
	v_fmac_f32_e32 v37, v38, v35
	v_fma_f32 v34, -v34, v37, v36
	v_div_fmas_f32 v34, v34, v35, v37
	v_div_fixup_f32 v22, v34, v33, v22
	v_cvt_pk_bf16_f32 v22, v27, v22
	ds_write_b16 v21, v22 offset:44
	ds_write_b16_d16_hi v18, v22 offset:44
	v_add_u32_e32 v22, 25, v19
	v_cmp_lt_i32_e32 vcc, s0, v19
	v_cmp_gt_u32_e64 s[0:1], s14, v22
	s_and_b64 s[18:19], vcc, s[0:1]
	s_and_saveexec_b64 s[0:1], s[18:19]
	s_cbranch_execz .LBB0_520
	v_mad_u64_u32 v[32:33], s[18:19], v22, s50, v[16:17]
	v_mov_b32_e32 v32, v154
.LBB0_520:
	s_or_b64 exec, exec, s[0:1]
	v_fma_f32 v28, v10, v28, v4
	v_fmac_f32_e32 v28, v12, v29
	v_fmac_f32_e32 v28, v6, v30
	s_waitcnt vmcnt(0)
	v_lshlrev_b32_e32 v27, 16, v32
	v_fmac_f32_e32 v28, v8, v31
	v_fmac_f32_e32 v28, v14, v27
	v_and_b32_e32 v22, 0xffff0000, v32
	v_mul_f32_e32 v32, 0xbfb8aa3b, v28
	v_exp_f32_e32 v32, v32
	v_fma_f32 v23, v11, v23, v5
	v_fmac_f32_e32 v23, v13, v24
	v_fmac_f32_e32 v23, v7, v25
	v_add_f32_e32 v32, 1.0, v32
	v_div_scale_f32 v33, s[0:1], v32, v32, v28
	v_rcp_f32_e32 v34, v33
	v_fmac_f32_e32 v23, v9, v26
	v_fmac_f32_e32 v23, v15, v22
	v_fma_f32 v35, -v33, v34, 1.0
	v_fmac_f32_e32 v34, v35, v34
	v_div_scale_f32 v35, vcc, v28, v32, v28
	v_mul_f32_e32 v36, v35, v34
	v_fma_f32 v37, -v33, v36, v35
	v_fmac_f32_e32 v36, v37, v34
	v_fma_f32 v33, -v33, v36, v35
	v_div_fmas_f32 v33, v33, v34, v36
	v_div_fixup_f32 v28, v33, v32, v28
	v_mul_f32_e32 v32, 0xbfb8aa3b, v23
	v_exp_f32_e32 v32, v32
	s_nop 0
	v_add_f32_e32 v32, 1.0, v32
	v_div_scale_f32 v33, s[0:1], v32, v32, v23
	v_rcp_f32_e32 v34, v33
	s_movk_i32 s0, 0xffe5
	v_fma_f32 v35, -v33, v34, 1.0
	v_fmac_f32_e32 v34, v35, v34
	v_div_scale_f32 v35, vcc, v23, v32, v23
	v_mul_f32_e32 v36, v35, v34
	v_fma_f32 v37, -v33, v36, v35
	v_fmac_f32_e32 v36, v37, v34
	v_fma_f32 v33, -v33, v36, v35
	v_div_fmas_f32 v33, v33, v34, v36
	v_div_fixup_f32 v23, v33, v32, v23
	v_cvt_pk_bf16_f32 v23, v28, v23
	ds_write_b16 v21, v23 offset:46
	ds_write_b16_d16_hi v18, v23 offset:46
	v_add_u32_e32 v23, 26, v19
	v_cmp_lt_i32_e32 vcc, s0, v19
	v_cmp_gt_u32_e64 s[0:1], s14, v23
	s_and_b64 s[18:19], vcc, s[0:1]
	v_mov_b32_e32 v32, 0
	v_mov_b32_e32 v33, 0
	s_and_saveexec_b64 s[0:1], s[18:19]
	s_cbranch_execz .LBB0_522
	v_mad_u64_u32 v[34:35], s[18:19], v23, s50, v[16:17]
	v_mov_b32_e32 v33, v155
; #define LAS __attribute__((address_space(3)))
; __device__ __forceinline__ unsigned pk2(float lo, float hi) { unsigned r; asm volatile("v_cvt_pk_bf16_f32 %0, %1, %2" : "=v"(r) : "v"(lo), "v"(hi)); return r; }
; __device__ __forceinline__ float lo16(unsigned w) { return __uint_as_float(w << 16); }
; __device__ __forceinline__ float hi16(unsigned w) { return __uint_as_float(w & 0xffff0000u); }
; __device__ __forceinline__ float siluf_(float x) { return x / (1.0f + __expf(-x)); }
; template <class Put>
; __device__ __forceinline__ void conv_pair32(const bf16* Pseq  , int L, int p0, int xch, const float* cw, const float* cb, const Put& put) {
;     ...
;     for (int i = 0; i < 36; ++i) {
;         const int pos = p0 + i - 2;
;         unsigned raw = 0u;
;         if (pos >= 0 && pos < L) raw = *(const unsigned*)(Pseq + (size_t)pos * LDP + xch);
;         a0 = a1; a1 = a2; a2 = a3; a3 = a4; a4 = lo16(raw);
;         c0 = c1; c1 = c2; c2 = c3; c3 = c4; c4 = hi16(raw);
;         if (i >= 4) {
;             const float v0 = b0 + w0[0] * a0 + w0[1] * a1 + w0[2] * a2 + w0[3] * a3 + w0[4] * a4;
;             const float v1 = b1 + w1[0] * c0 + w1[1] * c1 + w1[2] * c2 + w1[3] * c3 + w1[4] * c4;
;             put(i - 4, siluf_(v0), siluf_(v1));
;         }
; __device__ __forceinline__ void ssd_state_unit(const Params& p, int layer, LAS unsigned char* lds, int b, int cc, int g) {
;     ...
;         conv_pair32(Pm + (size_t)G.Rseq0 * LDP + C_BX, G.L, G.pos0 + q * 32, xch, cw, cb, [&](int l, float v0, float v1) {
;             const unsigned pk = pk2(v0, v1); const int ll = q * 32 + l;
;             *(LAS unsigned short*)(dst + ll * 2) = (unsigned short)(pk & 0xffffu); *(LAS unsigned short*)(dst + pitch + ll * 2) = (unsigned short)(pk >> 16); });
.LBB0_522:
	s_or_b64 exec, exec, s[0:1]
	v_fma_f32 v29, v10, v29, v4
	v_fmac_f32_e32 v29, v12, v30
	v_fmac_f32_e32 v29, v6, v31
	s_waitcnt vmcnt(0)
	v_lshlrev_b32_e32 v28, 16, v33
	v_fmac_f32_e32 v29, v8, v27
	v_fmac_f32_e32 v29, v14, v28
	v_and_b32_e32 v23, 0xffff0000, v33
	v_mul_f32_e32 v33, 0xbfb8aa3b, v29
	v_exp_f32_e32 v33, v33
	v_fma_f32 v24, v11, v24, v5
	v_fmac_f32_e32 v24, v13, v25
	v_fmac_f32_e32 v24, v7, v26
	v_add_f32_e32 v33, 1.0, v33
	v_div_scale_f32 v34, s[0:1], v33, v33, v29
	v_rcp_f32_e32 v35, v34
	v_fmac_f32_e32 v24, v9, v22
	v_fmac_f32_e32 v24, v15, v23
	v_fma_f32 v36, -v34, v35, 1.0
	v_fmac_f32_e32 v35, v36, v35
	v_div_scale_f32 v36, vcc, v29, v33, v29
	v_mul_f32_e32 v37, v36, v35
	v_fma_f32 v38, -v34, v37, v36
	v_fmac_f32_e32 v37, v38, v35
	v_fma_f32 v34, -v34, v37, v36
	v_div_fmas_f32 v34, v34, v35, v37
	v_div_fixup_f32 v29, v34, v33, v29
	v_mul_f32_e32 v33, 0xbfb8aa3b, v24
	v_exp_f32_e32 v33, v33
	s_nop 0
	v_add_f32_e32 v33, 1.0, v33
	v_div_scale_f32 v34, s[0:1], v33, v33, v24
	v_rcp_f32_e32 v35, v34
	s_movk_i32 s0, 0xffe4
	v_fma_f32 v36, -v34, v35, 1.0
	v_fmac_f32_e32 v35, v36, v35
	v_div_scale_f32 v36, vcc, v24, v33, v24
	v_mul_f32_e32 v37, v36, v35
	v_fma_f32 v38, -v34, v37, v36
	v_fmac_f32_e32 v37, v38, v35
	v_fma_f32 v34, -v34, v37, v36
	v_div_fmas_f32 v34, v34, v35, v37
	v_div_fixup_f32 v24, v34, v33, v24
	v_cvt_pk_bf16_f32 v24, v29, v24
	ds_write_b16 v21, v24 offset:48
	ds_write_b16_d16_hi v18, v24 offset:48
	v_add_u32_e32 v24, 27, v19
	v_cmp_lt_i32_e32 vcc, s0, v19
	v_cmp_gt_u32_e64 s[0:1], s14, v24
	s_and_b64 s[18:19], vcc, s[0:1]
	s_and_saveexec_b64 s[0:1], s[18:19]
	s_cbranch_execz .LBB0_524
	v_mad_u64_u32 v[32:33], s[18:19], v24, s50, v[16:17]
	v_mov_b32_e32 v32, v156
.LBB0_524:
	s_or_b64 exec, exec, s[0:1]
	v_fma_f32 v30, v10, v30, v4
	v_fmac_f32_e32 v30, v12, v31
	v_fmac_f32_e32 v30, v6, v27
	s_waitcnt vmcnt(0)
	v_lshlrev_b32_e32 v29, 16, v32
	v_fmac_f32_e32 v30, v8, v28
	v_fmac_f32_e32 v30, v14, v29
	v_and_b32_e32 v24, 0xffff0000, v32
	v_mul_f32_e32 v32, 0xbfb8aa3b, v30
	v_exp_f32_e32 v32, v32
	v_fma_f32 v25, v11, v25, v5
	v_fmac_f32_e32 v25, v13, v26
	v_fmac_f32_e32 v25, v7, v22
	v_add_f32_e32 v32, 1.0, v32
	v_div_scale_f32 v33, s[0:1], v32, v32, v30
	v_rcp_f32_e32 v34, v33
	v_fmac_f32_e32 v25, v9, v23
	v_fmac_f32_e32 v25, v15, v24
	v_fma_f32 v35, -v33, v34, 1.0
	v_fmac_f32_e32 v34, v35, v34
	v_div_scale_f32 v35, vcc, v30, v32, v30
	v_mul_f32_e32 v36, v35, v34
	v_fma_f32 v37, -v33, v36, v35
	v_fmac_f32_e32 v36, v37, v34
	v_fma_f32 v33, -v33, v36, v35
	v_div_fmas_f32 v33, v33, v34, v36
	v_div_fixup_f32 v30, v33, v32, v30
	v_mul_f32_e32 v32, 0xbfb8aa3b, v25
	v_exp_f32_e32 v32, v32
	s_nop 0
	v_add_f32_e32 v32, 1.0, v32
	v_div_scale_f32 v33, s[0:1], v32, v32, v25
	v_rcp_f32_e32 v34, v33
	s_movk_i32 s0, 0xffe3
	v_fma_f32 v35, -v33, v34, 1.0
	v_fmac_f32_e32 v34, v35, v34
	v_div_scale_f32 v35, vcc, v25, v32, v25
	v_mul_f32_e32 v36, v35, v34
	v_fma_f32 v37, -v33, v36, v35
	v_fmac_f32_e32 v36, v37, v34
	v_fma_f32 v33, -v33, v36, v35
	v_div_fmas_f32 v33, v33, v34, v36
	v_div_fixup_f32 v25, v33, v32, v25
	v_cvt_pk_bf16_f32 v25, v30, v25
	ds_write_b16 v21, v25 offset:50
	ds_write_b16_d16_hi v18, v25 offset:50
	v_add_u32_e32 v25, 28, v19
	v_cmp_lt_i32_e32 vcc, s0, v19
	v_cmp_gt_u32_e64 s[0:1], s14, v25
	s_and_b64 s[18:19], vcc, s[0:1]
	v_mov_b32_e32 v32, 0
	v_mov_b32_e32 v33, 0
	s_and_saveexec_b64 s[0:1], s[18:19]
	s_cbranch_execz .LBB0_526
	v_mad_u64_u32 v[34:35], s[18:19], v25, s50, v[16:17]
	v_mov_b32_e32 v33, v157
.LBB0_526:
	s_or_b64 exec, exec, s[0:1]
	v_fma_f32 v31, v10, v31, v4
	v_fmac_f32_e32 v31, v12, v27
	v_fmac_f32_e32 v31, v6, v28
	s_waitcnt vmcnt(0)
	v_lshlrev_b32_e32 v30, 16, v33
	v_fmac_f32_e32 v31, v8, v29
	v_fmac_f32_e32 v31, v14, v30
	v_and_b32_e32 v25, 0xffff0000, v33
	v_mul_f32_e32 v33, 0xbfb8aa3b, v31
	v_exp_f32_e32 v33, v33
	v_fma_f32 v26, v11, v26, v5
	v_fmac_f32_e32 v26, v13, v22
	v_fmac_f32_e32 v26, v7, v23
	v_add_f32_e32 v33, 1.0, v33
	v_div_scale_f32 v34, s[0:1], v33, v33, v31
	v_rcp_f32_e32 v35, v34
	v_fmac_f32_e32 v26, v9, v24
	v_fmac_f32_e32 v26, v15, v25
	v_fma_f32 v36, -v34, v35, 1.0
	v_fmac_f32_e32 v35, v36, v35
	v_div_scale_f32 v36, vcc, v31, v33, v31
	v_mul_f32_e32 v37, v36, v35
	v_fma_f32 v38, -v34, v37, v36
	v_fmac_f32_e32 v37, v38, v35
	v_fma_f32 v34, -v34, v37, v36
	v_div_fmas_f32 v34, v34, v35, v37
	v_div_fixup_f32 v31, v34, v33, v31
	v_mul_f32_e32 v33, 0xbfb8aa3b, v26
	v_exp_f32_e32 v33, v33
	s_nop 0
	v_add_f32_e32 v33, 1.0, v33
	v_div_scale_f32 v34, s[0:1], v33, v33, v26
	v_rcp_f32_e32 v35, v34
	s_movk_i32 s0, 0xffe2
	v_fma_f32 v36, -v34, v35, 1.0
	v_fmac_f32_e32 v35, v36, v35
	v_div_scale_f32 v36, vcc, v26, v33, v26
	v_mul_f32_e32 v37, v36, v35
	v_fma_f32 v38, -v34, v37, v36
	v_fmac_f32_e32 v37, v38, v35
	v_fma_f32 v34, -v34, v37, v36
	v_div_fmas_f32 v34, v34, v35, v37
	v_div_fixup_f32 v26, v34, v33, v26
	v_cvt_pk_bf16_f32 v26, v31, v26
	ds_write_b16 v21, v26 offset:52
	ds_write_b16_d16_hi v18, v26 offset:52
	v_add_u32_e32 v26, 29, v19
	v_cmp_lt_i32_e32 vcc, s0, v19
	v_cmp_gt_u32_e64 s[0:1], s14, v26
	s_and_b64 s[18:19], vcc, s[0:1]
	s_and_saveexec_b64 s[0:1], s[18:19]
	s_cbranch_execz .LBB0_528
	v_mad_u64_u32 v[32:33], s[18:19], v26, s50, v[16:17]
	v_mov_b32_e32 v32, v158
; #define LAS __attribute__((address_space(3)))
; __device__ __forceinline__ unsigned pk2(float lo, float hi) { unsigned r; asm volatile("v_cvt_pk_bf16_f32 %0, %1, %2" : "=v"(r) : "v"(lo), "v"(hi)); return r; }
; __device__ __forceinline__ float lo16(unsigned w) { return __uint_as_float(w << 16); }
; __device__ __forceinline__ float hi16(unsigned w) { return __uint_as_float(w & 0xffff0000u); }
; __device__ __forceinline__ float siluf_(float x) { return x / (1.0f + __expf(-x)); }
; template <class Put>
; __device__ __forceinline__ void conv_pair32(const bf16* Pseq  , int L, int p0, int xch, const float* cw, const float* cb, const Put& put) {
;     ...
;     for (int i = 0; i < 36; ++i) {
;         const int pos = p0 + i - 2;
;         unsigned raw = 0u;
;         if (pos >= 0 && pos < L) raw = *(const unsigned*)(Pseq + (size_t)pos * LDP + xch);
;         a0 = a1; a1 = a2; a2 = a3; a3 = a4; a4 = lo16(raw);
;         c0 = c1; c1 = c2; c2 = c3; c3 = c4; c4 = hi16(raw);
;         if (i >= 4) {
;             const float v0 = b0 + w0[0] * a0 + w0[1] * a1 + w0[2] * a2 + w0[3] * a3 + w0[4] * a4;
;             const float v1 = b1 + w1[0] * c0 + w1[1] * c1 + w1[2] * c2 + w1[3] * c3 + w1[4] * c4;
;             put(i - 4, siluf_(v0), siluf_(v1));
;         }
; __device__ __forceinline__ void ssd_state_unit(const Params& p, int layer, LAS unsigned char* lds, int b, int cc, int g) {
;     ...
;         conv_pair32(Pm + (size_t)G.Rseq0 * LDP + C_BX, G.L, G.pos0 + q * 32, xch, cw, cb, [&](int l, float v0, float v1) {
;             const unsigned pk = pk2(v0, v1); const int ll = q * 32 + l;
;             *(LAS unsigned short*)(dst + ll * 2) = (unsigned short)(pk & 0xffffu); *(LAS unsigned short*)(dst + pitch + ll * 2) = (unsigned short)(pk >> 16); });
.LBB0_528:
	s_or_b64 exec, exec, s[0:1]
	v_fma_f32 v27, v10, v27, v4
	v_fmac_f32_e32 v27, v12, v28
	v_fmac_f32_e32 v27, v6, v29
	s_waitcnt vmcnt(0)
	v_lshlrev_b32_e32 v31, 16, v32
	v_fmac_f32_e32 v27, v8, v30
	v_fmac_f32_e32 v27, v14, v31
	v_and_b32_e32 v26, 0xffff0000, v32
	v_mul_f32_e32 v32, 0xbfb8aa3b, v27
	v_exp_f32_e32 v32, v32
	v_fma_f32 v22, v11, v22, v5
	v_fmac_f32_e32 v22, v13, v23
	v_fmac_f32_e32 v22, v7, v24
	v_add_f32_e32 v32, 1.0, v32
	v_div_scale_f32 v33, s[0:1], v32, v32, v27
	v_rcp_f32_e32 v34, v33
	v_fmac_f32_e32 v22, v9, v25
	v_fmac_f32_e32 v22, v15, v26
	v_fma_f32 v35, -v33, v34, 1.0
	v_fmac_f32_e32 v34, v35, v34
	v_div_scale_f32 v35, vcc, v27, v32, v27
	v_mul_f32_e32 v36, v35, v34
	v_fma_f32 v37, -v33, v36, v35
	v_fmac_f32_e32 v36, v37, v34
	v_fma_f32 v33, -v33, v36, v35
	v_div_fmas_f32 v33, v33, v34, v36
	v_div_fixup_f32 v27, v33, v32, v27
	v_mul_f32_e32 v32, 0xbfb8aa3b, v22
	v_exp_f32_e32 v32, v32
	s_nop 0
	v_add_f32_e32 v32, 1.0, v32
	v_div_scale_f32 v33, s[0:1], v32, v32, v22
	v_rcp_f32_e32 v34, v33
	s_movk_i32 s0, 0xffe1
	v_fma_f32 v35, -v33, v34, 1.0
	v_fmac_f32_e32 v34, v35, v34
	v_div_scale_f32 v35, vcc, v22, v32, v22
	v_mul_f32_e32 v36, v35, v34
	v_fma_f32 v37, -v33, v36, v35
	v_fmac_f32_e32 v36, v37, v34
	v_fma_f32 v33, -v33, v36, v35
	v_div_fmas_f32 v33, v33, v34, v36
	v_div_fixup_f32 v22, v33, v32, v22
	v_cvt_pk_bf16_f32 v22, v27, v22
	ds_write_b16 v21, v22 offset:54
	ds_write_b16_d16_hi v18, v22 offset:54
	v_add_u32_e32 v22, 30, v19
	v_cmp_lt_i32_e32 vcc, s0, v19
	v_cmp_gt_u32_e64 s[0:1], s14, v22
	s_and_b64 s[18:19], vcc, s[0:1]
	v_mov_b32_e32 v32, 0
	v_mov_b32_e32 v33, 0
	s_and_saveexec_b64 s[0:1], s[18:19]
	s_cbranch_execz .LBB0_530
	v_mad_u64_u32 v[34:35], s[18:19], v22, s50, v[16:17]
	v_mov_b32_e32 v33, v159
.LBB0_530:
	s_or_b64 exec, exec, s[0:1]
	v_fma_f32 v28, v10, v28, v4
	v_fmac_f32_e32 v28, v12, v29
	v_fmac_f32_e32 v28, v6, v30
	s_waitcnt vmcnt(0)
	v_lshlrev_b32_e32 v27, 16, v33
	v_fmac_f32_e32 v28, v8, v31
	v_fmac_f32_e32 v28, v14, v27
	v_and_b32_e32 v22, 0xffff0000, v33
	v_mul_f32_e32 v33, 0xbfb8aa3b, v28
	v_exp_f32_e32 v33, v33
	v_fma_f32 v23, v11, v23, v5
	v_fmac_f32_e32 v23, v13, v24
	v_fmac_f32_e32 v23, v7, v25
	v_add_f32_e32 v33, 1.0, v33
	v_div_scale_f32 v34, s[0:1], v33, v33, v28
	v_rcp_f32_e32 v35, v34
	v_fmac_f32_e32 v23, v9, v26
	v_fmac_f32_e32 v23, v15, v22
	v_fma_f32 v36, -v34, v35, 1.0
	v_fmac_f32_e32 v35, v36, v35
	v_div_scale_f32 v36, vcc, v28, v33, v28
	v_mul_f32_e32 v37, v36, v35
	v_fma_f32 v38, -v34, v37, v36
	v_fmac_f32_e32 v37, v38, v35
	v_fma_f32 v34, -v34, v37, v36
	v_div_fmas_f32 v34, v34, v35, v37
	v_div_fixup_f32 v28, v34, v33, v28
	v_mul_f32_e32 v33, 0xbfb8aa3b, v23
	v_exp_f32_e32 v33, v33
	s_nop 0
	v_add_f32_e32 v33, 1.0, v33
	v_div_scale_f32 v34, s[0:1], v33, v33, v23
	v_rcp_f32_e32 v35, v34
	s_movk_i32 s0, 0xffe0
	v_fma_f32 v36, -v34, v35, 1.0
	v_fmac_f32_e32 v35, v36, v35
	v_div_scale_f32 v36, vcc, v23, v33, v23
	v_mul_f32_e32 v37, v36, v35
	v_fma_f32 v38, -v34, v37, v36
	v_fmac_f32_e32 v37, v38, v35
	v_fma_f32 v34, -v34, v37, v36
	v_div_fmas_f32 v34, v34, v35, v37
	v_div_fixup_f32 v23, v34, v33, v23
	v_cvt_pk_bf16_f32 v23, v28, v23
	ds_write_b16 v21, v23 offset:56
	ds_write_b16_d16_hi v18, v23 offset:56
	v_add_u32_e32 v23, 31, v19
	v_cmp_lt_i32_e32 vcc, s0, v19
	v_cmp_gt_u32_e64 s[0:1], s14, v23
	s_and_b64 s[18:19], vcc, s[0:1]
	s_and_saveexec_b64 s[0:1], s[18:19]
	s_cbranch_execz .LBB0_532
	v_mad_u64_u32 v[32:33], s[18:19], v23, s50, v[16:17]
	v_mov_b32_e32 v32, v160
.LBB0_532:
	s_or_b64 exec, exec, s[0:1]
	v_fma_f32 v29, v10, v29, v4
	v_fmac_f32_e32 v29, v12, v30
	v_fmac_f32_e32 v29, v6, v31
	s_waitcnt vmcnt(0)
	v_lshlrev_b32_e32 v28, 16, v32
	v_fmac_f32_e32 v29, v8, v27
	v_fmac_f32_e32 v29, v14, v28
	v_and_b32_e32 v23, 0xffff0000, v32
	v_mul_f32_e32 v32, 0xbfb8aa3b, v29
	v_exp_f32_e32 v32, v32
	v_fma_f32 v24, v11, v24, v5
	v_fmac_f32_e32 v24, v13, v25
	v_fmac_f32_e32 v24, v7, v26
	v_add_f32_e32 v32, 1.0, v32
	v_div_scale_f32 v33, s[0:1], v32, v32, v29
	v_rcp_f32_e32 v34, v33
	v_fmac_f32_e32 v24, v9, v22
	v_fmac_f32_e32 v24, v15, v23
	v_fma_f32 v35, -v33, v34, 1.0
	v_fmac_f32_e32 v34, v35, v34
	v_div_scale_f32 v35, vcc, v29, v32, v29
	v_mul_f32_e32 v36, v35, v34
	v_fma_f32 v37, -v33, v36, v35
	v_fmac_f32_e32 v36, v37, v34
	v_fma_f32 v33, -v33, v36, v35
	v_div_fmas_f32 v33, v33, v34, v36
	v_div_fixup_f32 v29, v33, v32, v29
	v_mul_f32_e32 v32, 0xbfb8aa3b, v24
	v_exp_f32_e32 v32, v32
	s_nop 0
	v_add_f32_e32 v32, 1.0, v32
	v_div_scale_f32 v33, s[0:1], v32, v32, v24
	v_rcp_f32_e32 v34, v33
	s_movk_i32 s0, 0xffdf
	v_fma_f32 v35, -v33, v34, 1.0
	v_fmac_f32_e32 v34, v35, v34
	v_div_scale_f32 v35, vcc, v24, v32, v24
	v_mul_f32_e32 v36, v35, v34
	v_fma_f32 v37, -v33, v36, v35
	v_fmac_f32_e32 v36, v37, v34
	v_fma_f32 v33, -v33, v36, v35
	v_div_fmas_f32 v33, v33, v34, v36
	v_div_fixup_f32 v24, v33, v32, v24
	v_cvt_pk_bf16_f32 v24, v29, v24
	ds_write_b16 v21, v24 offset:58
	ds_write_b16_d16_hi v18, v24 offset:58
	v_add_u32_e32 v24, 32, v19
	v_cmp_lt_i32_e32 vcc, s0, v19
	v_cmp_gt_u32_e64 s[0:1], s14, v24
	s_and_b64 s[18:19], vcc, s[0:1]
	v_mov_b32_e32 v29, 0
	v_mov_b32_e32 v33, 0
	s_and_saveexec_b64 s[0:1], s[18:19]
	s_cbranch_execz .LBB0_534
	v_mad_u64_u32 v[32:33], s[18:19], v24, s50, v[16:17]
	v_mov_b32_e32 v33, v161
.LBB0_534:
	s_or_b64 exec, exec, s[0:1]
	v_fma_f32 v30, v10, v30, v4
	v_fmac_f32_e32 v30, v12, v31
	v_fmac_f32_e32 v30, v6, v27
	s_waitcnt vmcnt(0)
	v_lshlrev_b32_e32 v32, 16, v33
	v_fmac_f32_e32 v30, v8, v28
	v_fmac_f32_e32 v30, v14, v32
	v_and_b32_e32 v24, 0xffff0000, v33
	v_mul_f32_e32 v33, 0xbfb8aa3b, v30
	v_exp_f32_e32 v33, v33
	v_fma_f32 v25, v11, v25, v5
	v_fmac_f32_e32 v25, v13, v26
	v_fmac_f32_e32 v25, v7, v22
	v_add_f32_e32 v33, 1.0, v33
	v_div_scale_f32 v34, s[0:1], v33, v33, v30
	v_rcp_f32_e32 v35, v34
	v_fmac_f32_e32 v25, v9, v23
	v_fmac_f32_e32 v25, v15, v24
	v_fma_f32 v36, -v34, v35, 1.0
	v_fmac_f32_e32 v35, v36, v35
	v_div_scale_f32 v36, vcc, v30, v33, v30
	v_mul_f32_e32 v37, v36, v35
	v_fma_f32 v38, -v34, v37, v36
	v_fmac_f32_e32 v37, v38, v35
	v_fma_f32 v34, -v34, v37, v36
	v_div_fmas_f32 v34, v34, v35, v37
	v_div_fixup_f32 v30, v34, v33, v30
	v_mul_f32_e32 v33, 0xbfb8aa3b, v25
	v_exp_f32_e32 v33, v33
	s_nop 0
	v_add_f32_e32 v33, 1.0, v33
	v_div_scale_f32 v34, s[0:1], v33, v33, v25
	v_rcp_f32_e32 v35, v34
	s_movk_i32 s0, 0xffde
	v_fma_f32 v36, -v34, v35, 1.0
	v_fmac_f32_e32 v35, v36, v35
	v_div_scale_f32 v36, vcc, v25, v33, v25
	v_mul_f32_e32 v37, v36, v35
	v_fma_f32 v38, -v34, v37, v36
	v_fmac_f32_e32 v37, v38, v35
	v_fma_f32 v34, -v34, v37, v36
	v_div_fmas_f32 v34, v34, v35, v37
	v_div_fixup_f32 v25, v34, v33, v25
	v_cvt_pk_bf16_f32 v25, v30, v25
	ds_write_b16 v21, v25 offset:60
	ds_write_b16_d16_hi v18, v25 offset:60
	v_add_u32_e32 v25, 33, v19
	v_cmp_lt_i32_e32 vcc, s0, v19
	v_cmp_gt_u32_e64 s[0:1], s14, v25
	s_and_b64 s[18:19], vcc, s[0:1]
	s_and_saveexec_b64 s[0:1], s[18:19]
	s_cbranch_execz .LBB0_459
	v_mad_u64_u32 v[16:17], s[18:19], v25, s50, v[16:17]
	v_mov_b32_e32 v29, v162
	s_branch .LBB0_459

; #define LAS __attribute__((address_space(3)))
; __device__ __forceinline__ float max3f(float a, float b, float c) { float r; asm("v_max3_f32 %0, %1, %2, %3" : "=v"(r) : "v"(a), "v"(b), "v"(c)); return r; }
; #define MFMA16(a, b, c) __builtin_amdgcn_mfma_f32_16x16x32_bf16((a), (b), (c), 0, 0, 0)
; template <int NS, int DV, class MaskF> ...
;     ...
;     f32x4 s[NS][4];
; #pragma unroll
;     for (int st = 0; st < NS; ++st)
; #pragma unroll
;         for (int kt = 0; kt < 4; ++kt) {
;             const LAS unsigned char* kp = bufK + (kslot[st] * 64 + kt * 16 + fr) * AT_PITCH + g * 16;
;             const bf16x8 a0 = *(const LAS bf16x8*)kp, a1 = *(const LAS bf16x8*)(kp + 64);
;             const float nm = -mrun[st];
;             f32x4 z = {nm, nm, nm, nm};
;             z = MFMA16(a0, qf[st][0], z); z = MFMA16(a1, qf[st][1], z);
;             s[st][kt] = z;
;         }
;     if (masked) {
; #pragma unroll
;         for (int st = 0; st < NS; ++st)
; #pragma unroll
;             for (int kt = 0; kt < 4; ++kt)
; #pragma unroll
;                 for (int i = 0; i < 4; ++i) s[st][kt][i] = mf(s[st][kt][i], st, kt * 16 + g * 4 + i);
;     } else {
;         __builtin_amdgcn_sched_group_barrier(0x100, 4, 0);
; #pragma unroll
;         for (int i = 0; i < NS * 8; ++i) { __builtin_amdgcn_sched_group_barrier(0x008, 1, 0); __builtin_amdgcn_sched_group_barrier(0x100, 1, 0); }
;     }
;     __builtin_amdgcn_sched_barrier(0);
;     float mxs[NS]; bool slow = first;
; #pragma unroll
;     for (int st = 0; st < NS; ++st) {
;         float mx = max3f(s[st][0][0], s[st][0][1], s[st][0][2]);
;         mx = max3f(mx, s[st][0][3], s[st][1][0]); mx = max3f(mx, s[st][1][1], s[st][1][2]); mx = max3f(mx, s[st][1][3], s[st][2][0]);
;         mx = max3f(mx, s[st][2][1], s[st][2][2]); mx = max3f(mx, s[st][2][3], s[st][3][0]); mx = max3f(mx, s[st][3][1], s[st][3][2]); mx = max3f(mx, s[st][3][3], mx);
;         mx = max3f(mx, __shfl_xor(mx, 16), mx); mx = max3f(mx, __shfl_xor(mx, 32), mx);
;         mxs[st] = mx; slow = slow || (mx > 8.0f);
;     }
.LBB0_650:
	s_mul_i32 s14, s13, 0xa000
	v_add_u32_e32 v190, s14, v227
	ds_read_b128 v[146:149], v190
	ds_read_b128 v[150:153], v190 offset:64
	ds_read_b128 v[154:157], v190 offset:2560
	ds_read_b128 v[158:161], v190 offset:2624
	ds_read_b128 v[182:185], v190 offset:5120
	ds_read_b128 v[186:189], v190 offset:5184
	v_xor_b32_e32 v126, 0x80000000, v173
	v_xor_b32_e32 v138, 0x80000000, v172
	v_mov_b32_e32 v127, v126
	v_mov_b32_e32 v128, v126
	v_mov_b32_e32 v129, v126
	v_mov_b32_e32 v139, v138
	v_mov_b32_e32 v140, v138
	v_mov_b32_e32 v141, v138
	s_mul_i32 s15, s15, 0xa000
	s_add_i32 s15, s15, 0
	s_waitcnt lgkmcnt(5)
	v_mfma_f32_16x16x32_bf16 v[114:117], v[146:149], v[2:5], v[126:129]
	ds_read_b128 v[146:149], v190 offset:7680
	s_waitcnt lgkmcnt(5)
	v_mfma_f32_16x16x32_bf16 v[114:117], v[150:153], v[6:9], v[114:117]
	ds_read_b128 v[150:153], v190 offset:7744
	s_waitcnt lgkmcnt(5)
	v_mfma_f32_16x16x32_bf16 v[118:121], v[154:157], v[2:5], v[126:129]
	ds_read_b128 v[154:157], v190 offset:10240
	s_waitcnt lgkmcnt(5)
	v_mfma_f32_16x16x32_bf16 v[118:121], v[158:161], v[6:9], v[118:121]
	ds_read_b128 v[158:161], v190 offset:10304
	s_waitcnt lgkmcnt(5)
	v_mfma_f32_16x16x32_bf16 v[122:125], v[182:185], v[2:5], v[126:129]
	ds_read_b128 v[182:185], v190 offset:12800
	s_waitcnt lgkmcnt(5)
	v_mfma_f32_16x16x32_bf16 v[122:125], v[186:189], v[6:9], v[122:125]
	ds_read_b128 v[186:189], v190 offset:12864
	s_waitcnt lgkmcnt(5)
	v_mfma_f32_16x16x32_bf16 v[126:129], v[146:149], v[2:5], v[126:129]
	ds_read_b128 v[146:149], v190 offset:15360
	s_waitcnt lgkmcnt(5)
	v_mfma_f32_16x16x32_bf16 v[126:129], v[150:153], v[6:9], v[126:129]
	ds_read_b128 v[150:153], v190 offset:15424
	s_waitcnt lgkmcnt(5)
	v_mfma_f32_16x16x32_bf16 v[134:137], v[154:157], v[10:13], v[138:141]
	ds_read_b128 v[154:157], v190 offset:17920
	s_waitcnt lgkmcnt(5)
	v_mfma_f32_16x16x32_bf16 v[134:137], v[158:161], v[14:17], v[134:137]
	ds_read_b128 v[158:161], v190 offset:17984
	s_waitcnt lgkmcnt(5)
	v_mfma_f32_16x16x32_bf16 v[142:145], v[182:185], v[10:13], v[138:141]
	s_waitcnt lgkmcnt(4)
	v_mfma_f32_16x16x32_bf16 v[142:145], v[186:189], v[14:17], v[142:145]
	s_waitcnt lgkmcnt(3)
	v_mfma_f32_16x16x32_bf16 v[130:133], v[146:149], v[10:13], v[138:141]
	s_waitcnt lgkmcnt(2)
	v_mfma_f32_16x16x32_bf16 v[130:133], v[150:153], v[14:17], v[130:133]
	s_waitcnt lgkmcnt(1)
	v_mfma_f32_16x16x32_bf16 v[138:141], v[154:157], v[10:13], v[138:141]
	s_waitcnt lgkmcnt(0)
	v_mfma_f32_16x16x32_bf16 v[138:141], v[158:161], v[14:17], v[138:141]
	v_max3_f32 v146, v114, v115, v116
	v_max3_f32 v148, v134, v135, v136
	s_mov_b32 s16, 0x41000000
	v_max3_f32 v146, v146, v117, v118
	v_max3_f32 v148, v148, v137, v142
	v_add3_u32 v179, s15, v226, v0
	v_max3_f32 v146, v146, v119, v120
	v_max3_f32 v148, v148, v143, v144
	v_add3_u32 v180, s15, v225, v0
	v_max3_f32 v146, v146, v121, v122
	v_max3_f32 v148, v148, v145, v130
	v_add3_u32 v178, s15, v224, v0
	v_max3_f32 v146, v146, v123, v124
	v_max3_f32 v148, v148, v131, v132
	s_nop 0
	v_max3_f32 v146, v146, v125, v126
	v_max3_f32 v148, v148, v133, v138
	s_nop 0
	v_max3_f32 v146, v146, v127, v128
	v_max3_f32 v148, v148, v139, v140
	s_nop 0
	v_max3_f32 v146, v146, v129, v146
	v_max3_f32 v148, v148, v141, v148
	v_mov_b32_e32 v147, v146
	v_mov_b32_e32 v149, v148
	s_nop 1
	v_permlane16_swap_b32_e32 v146, v147
	v_permlane16_swap_b32_e32 v148, v149
	v_max_f32_e32 v146, v146, v147
	v_max_f32_e32 v148, v148, v149
	v_mov_b32_e32 v147, v146
	v_mov_b32_e32 v149, v148
	s_nop 1
	v_permlane32_swap_b32_e32 v146, v147
	v_permlane32_swap_b32_e32 v148, v149
	v_max_f32_e32 v147, v146, v147
	v_max_f32_e32 v146, v148, v149
	s_nop 0
	v_max_f32_e32 v148, v146, v146
	v_max_f32_e32 v149, v147, v147
	v_max_f32_e32 v150, v149, v148
	v_cmp_lt_f32_e32 vcc, s16, v150
	s_cbranch_vccz .LBB0_652
; #define LAS __attribute__((address_space(3)))
; __device__ __forceinline__ float ex2(float x) { return __builtin_amdgcn_exp2f(x); }
; #define MFMA16(a, b, c) __builtin_amdgcn_mfma_f32_16x16x32_bf16((a), (b), (c), 0, 0, 0)
; template <int NS, int DV, class MaskF> ...
;     ...
;     if (__any(slow)) {
; #pragma unroll
;         for (int dt = 0; dt < DV / 16; ++dt)
; #pragma unroll
;             for (int j = 0; j < 2; ++j) {
;                 const bf16x8 va = *(const LAS bf16x8*)(bufV + (128 + vrow0 + dt * 16 + fr) * AT_PITCH + (j * 32 + g * 8) * 2);
; #pragma unroll
;                 for (int st = 0; st < NS; ++st) o[st][dt] = MFMA16(va, pkp[st][j], o[st][dt]);
;             }
; #pragma unroll
;         for (int st = 0; st < NS; ++st) {
;             const float d = mxs[st] < -1e20f ? 0.f : (first ? mxs[st] : fmaxf(mxs[st], 0.f));
;             mrun[st] += d; const float alpha = ex2(-d);
;             lrun[st] *= alpha;
; #pragma unroll
;             for (int kt = 0; kt < 4; ++kt) s[st][kt] = s[st][kt] - d;
; #pragma unroll
;             for (int dt = 0; dt < DV / 16; ++dt) o[st][dt] = o[st][dt] * alpha;
;             pkp[st][0] = (bf16x8){0, 0, 0, 0, 0, 0, 0, 0}; pkp[st][1] = pkp[st][0];
;         }
	ds_read_b128 v[150:153], v179 offset:20480
	s_mov_b32 s15, 0xe0ad78ec
	v_cmp_ngt_f32_e32 vcc, s15, v147
	s_waitcnt lgkmcnt(0)
	v_mfma_f32_16x16x32_bf16 v[38:41], v[150:153], v[54:57], v[38:41]
	v_mfma_f32_16x16x32_bf16 v[78:81], v[150:153], v[98:101], v[78:81]
	ds_read_b128 v[150:153], v179 offset:20544
	s_waitcnt lgkmcnt(0)
	v_mfma_f32_16x16x32_bf16 v[38:41], v[150:153], v[46:49], v[38:41]
	v_mfma_f32_16x16x32_bf16 v[78:81], v[150:153], v[70:73], v[78:81]
	ds_read_b128 v[150:153], v179 offset:23040
	s_waitcnt lgkmcnt(0)
	v_mfma_f32_16x16x32_bf16 v[34:37], v[150:153], v[54:57], v[34:37]
	v_mfma_f32_16x16x32_bf16 v[74:77], v[150:153], v[98:101], v[74:77]
	ds_read_b128 v[150:153], v179 offset:23104
	s_waitcnt lgkmcnt(0)
	v_mfma_f32_16x16x32_bf16 v[34:37], v[150:153], v[46:49], v[34:37]
	v_mfma_f32_16x16x32_bf16 v[74:77], v[150:153], v[70:73], v[74:77]
	ds_read_b128 v[150:153], v179 offset:25600
	s_waitcnt lgkmcnt(0)
	v_mfma_f32_16x16x32_bf16 v[42:45], v[150:153], v[54:57], v[42:45]
	v_mfma_f32_16x16x32_bf16 v[82:85], v[150:153], v[98:101], v[82:85]
	ds_read_b128 v[150:153], v179 offset:25664
	s_waitcnt lgkmcnt(0)
	v_mfma_f32_16x16x32_bf16 v[42:45], v[150:153], v[46:49], v[42:45]
	v_mfma_f32_16x16x32_bf16 v[82:85], v[150:153], v[70:73], v[82:85]
	ds_read_b128 v[150:153], v180 offset:20480
	s_waitcnt lgkmcnt(0)
	v_mfma_f32_16x16x32_bf16 v[50:53], v[150:153], v[54:57], v[50:53]
	v_mfma_f32_16x16x32_bf16 v[86:89], v[150:153], v[98:101], v[86:89]
	ds_read_b128 v[150:153], v180 offset:20544
	s_waitcnt lgkmcnt(0)
	v_mfma_f32_16x16x32_bf16 v[50:53], v[150:153], v[46:49], v[50:53]
	v_mfma_f32_16x16x32_bf16 v[86:89], v[150:153], v[70:73], v[86:89]
	ds_read_b128 v[150:153], v179 offset:30720
	s_waitcnt lgkmcnt(0)
	v_mfma_f32_16x16x32_bf16 v[62:65], v[150:153], v[54:57], v[62:65]
	v_mfma_f32_16x16x32_bf16 v[94:97], v[150:153], v[98:101], v[94:97]
	ds_read_b128 v[150:153], v179 offset:30784
	s_waitcnt lgkmcnt(0)
	v_mfma_f32_16x16x32_bf16 v[62:65], v[150:153], v[46:49], v[62:65]
	v_mfma_f32_16x16x32_bf16 v[94:97], v[150:153], v[70:73], v[94:97]
	ds_read_b128 v[150:153], v179 offset:33280
	s_waitcnt lgkmcnt(0)
	v_mfma_f32_16x16x32_bf16 v[58:61], v[150:153], v[54:57], v[58:61]
	v_mfma_f32_16x16x32_bf16 v[90:93], v[150:153], v[98:101], v[90:93]
	ds_read_b128 v[150:153], v179 offset:33344
	s_waitcnt lgkmcnt(0)
	v_mfma_f32_16x16x32_bf16 v[58:61], v[150:153], v[46:49], v[58:61]
	v_mfma_f32_16x16x32_bf16 v[90:93], v[150:153], v[70:73], v[90:93]
	ds_read_b128 v[150:153], v179 offset:35840
	s_waitcnt lgkmcnt(0)
	v_mfma_f32_16x16x32_bf16 v[66:69], v[150:153], v[54:57], v[66:69]
	v_mfma_f32_16x16x32_bf16 v[102:105], v[150:153], v[98:101], v[102:105]
	ds_read_b128 v[150:153], v179 offset:35904
	s_waitcnt lgkmcnt(0)
	v_mfma_f32_16x16x32_bf16 v[66:69], v[150:153], v[46:49], v[66:69]
	v_mfma_f32_16x16x32_bf16 v[102:105], v[150:153], v[70:73], v[102:105]
	ds_read_b128 v[150:153], v178 offset:20480
	s_waitcnt lgkmcnt(0)
	v_mfma_f32_16x16x32_bf16 v[54:57], v[150:153], v[54:57], v[106:109]
	s_nop 2
	ds_read_b128 v[106:109], v178 offset:20544
	v_mfma_f32_16x16x32_bf16 v[98:101], v[150:153], v[98:101], v[110:113]
	s_waitcnt lgkmcnt(0)
	v_mfma_f32_16x16x32_bf16 v[54:57], v[106:109], v[46:49], v[54:57]
	v_mfma_f32_16x16x32_bf16 v[46:49], v[106:109], v[70:73], v[98:101]
	v_max_f32_e32 v70, 0, v149
	v_max_f32_e32 v72, 0, v148
	v_cndmask_b32_e32 v71, 0, v70, vcc
	v_cmp_ngt_f32_e32 vcc, s15, v146
	v_sub_f32_e32 v114, v114, v71
	v_sub_f32_e32 v115, v115, v71
	v_cndmask_b32_e32 v70, 0, v72, vcc
	v_exp_f32_e64 v72, -v71
	v_pk_add_f32 v[172:173], v[172:173], v[70:71]
	v_sub_f32_e32 v134, v134, v70
	v_sub_f32_e32 v135, v135, v70
	v_pk_mul_f32 v[106:107], v[72:73], v[54:55] op_sel_hi:[0,1]
	v_exp_f32_e64 v54, -v70
	v_mov_b32_e32 v55, v72
	v_sub_f32_e32 v136, v136, v70
	v_sub_f32_e32 v137, v137, v70
	v_sub_f32_e32 v142, v142, v70
	v_sub_f32_e32 v143, v143, v70
	v_sub_f32_e32 v144, v144, v70
	v_sub_f32_e32 v145, v145, v70
	v_sub_f32_e32 v130, v130, v70
	v_sub_f32_e32 v131, v131, v70
	v_sub_f32_e32 v132, v132, v70
	v_sub_f32_e32 v133, v133, v70
	v_sub_f32_e32 v138, v138, v70
	v_sub_f32_e32 v139, v139, v70
	v_sub_f32_e32 v140, v140, v70
	v_sub_f32_e32 v141, v141, v70
	v_mov_b32_e32 v70, 0
	v_sub_f32_e32 v116, v116, v71
	v_sub_f32_e32 v117, v117, v71
	v_sub_f32_e32 v118, v118, v71
	v_sub_f32_e32 v119, v119, v71
	v_sub_f32_e32 v120, v120, v71
	v_sub_f32_e32 v121, v121, v71
	v_sub_f32_e32 v122, v122, v71
	v_sub_f32_e32 v123, v123, v71
	v_sub_f32_e32 v124, v124, v71
	v_sub_f32_e32 v125, v125, v71
	v_sub_f32_e32 v126, v126, v71
	v_sub_f32_e32 v127, v127, v71
	v_sub_f32_e32 v128, v128, v71
	v_sub_f32_e32 v129, v129, v71
	v_pk_mul_f32 v[40:41], v[72:73], v[40:41] op_sel_hi:[0,1]
	v_pk_mul_f32 v[38:39], v[72:73], v[38:39] op_sel_hi:[0,1]
	v_pk_mul_f32 v[36:37], v[72:73], v[36:37] op_sel_hi:[0,1]
	v_pk_mul_f32 v[34:35], v[72:73], v[34:35] op_sel_hi:[0,1]
	v_pk_mul_f32 v[44:45], v[72:73], v[44:45] op_sel_hi:[0,1]
	v_pk_mul_f32 v[42:43], v[72:73], v[42:43] op_sel_hi:[0,1]
	v_pk_mul_f32 v[52:53], v[72:73], v[52:53] op_sel_hi:[0,1]
	v_pk_mul_f32 v[50:51], v[72:73], v[50:51] op_sel_hi:[0,1]
	v_pk_mul_f32 v[64:65], v[72:73], v[64:65] op_sel_hi:[0,1]
	v_pk_mul_f32 v[62:63], v[72:73], v[62:63] op_sel_hi:[0,1]
	v_pk_mul_f32 v[60:61], v[72:73], v[60:61] op_sel_hi:[0,1]
	v_pk_mul_f32 v[58:59], v[72:73], v[58:59] op_sel_hi:[0,1]
	v_pk_mul_f32 v[68:69], v[72:73], v[68:69] op_sel_hi:[0,1]
	v_pk_mul_f32 v[66:67], v[72:73], v[66:67] op_sel_hi:[0,1]
	v_pk_mul_f32 v[108:109], v[72:73], v[56:57] op_sel_hi:[0,1]
	v_pk_mul_f32 v[174:175], v[174:175], v[54:55]
	v_pk_mul_f32 v[80:81], v[54:55], v[80:81] op_sel_hi:[0,1]
	v_pk_mul_f32 v[78:79], v[54:55], v[78:79] op_sel_hi:[0,1]
	v_pk_mul_f32 v[76:77], v[54:55], v[76:77] op_sel_hi:[0,1]
	v_pk_mul_f32 v[74:75], v[54:55], v[74:75] op_sel_hi:[0,1]
	v_pk_mul_f32 v[84:85], v[54:55], v[84:85] op_sel_hi:[0,1]
	v_pk_mul_f32 v[82:83], v[54:55], v[82:83] op_sel_hi:[0,1]
	v_pk_mul_f32 v[88:89], v[54:55], v[88:89] op_sel_hi:[0,1]
	v_pk_mul_f32 v[86:87], v[54:55], v[86:87] op_sel_hi:[0,1]
	v_pk_mul_f32 v[96:97], v[54:55], v[96:97] op_sel_hi:[0,1]
	v_pk_mul_f32 v[94:95], v[54:55], v[94:95] op_sel_hi:[0,1]
	v_pk_mul_f32 v[92:93], v[54:55], v[92:93] op_sel_hi:[0,1]
	v_pk_mul_f32 v[90:91], v[54:55], v[90:91] op_sel_hi:[0,1]
	v_pk_mul_f32 v[104:105], v[54:55], v[104:105] op_sel_hi:[0,1]
	v_pk_mul_f32 v[102:103], v[54:55], v[102:103] op_sel_hi:[0,1]
	v_pk_mul_f32 v[112:113], v[54:55], v[48:49] op_sel_hi:[0,1]
	v_pk_mul_f32 v[110:111], v[54:55], v[46:47] op_sel_hi:[0,1]
	v_mov_b32_e32 v71, v70
	v_mov_b32_e32 v72, v70
	v_mov_b32_e32 v73, v70
	v_mov_b32_e32 v98, v70
	v_mov_b32_e32 v99, v70
	v_mov_b32_e32 v100, v70
	v_mov_b32_e32 v101, v70
	v_mov_b32_e32 v46, v70
	v_mov_b32_e32 v47, v70
	v_mov_b32_e32 v48, v70
	v_mov_b32_e32 v49, v70
	v_mov_b32_e32 v54, v70
	v_mov_b32_e32 v55, v70
	v_mov_b32_e32 v56, v70
	v_mov_b32_e32 v57, v70
